# v40 with the seven GEMM K-loop heads aligned to 64 bytes (code placement test)
# speedup vs baseline: 1.0010x; 1.0010x over previous
.LBB0_145:
	s_ashr_i32 s17, s16, 31
	s_lshl_b64 s[18:19], s[16:17], 19
	s_add_u32 s18, s36, s18
	s_addc_u32 s19, s37, s19
	s_and_b64 s[20:21], s[2:3], exec
	s_cselect_b32 s17, s19, s25
	s_cselect_b32 s50, s18, s24
	s_ashr_i32 s15, s14, 31
	s_lshl_b64 s[20:21], s[14:15], 19
	s_add_u32 s20, s34, s20
	s_addc_u32 s21, s35, s21
	s_and_b64 s[28:29], s[2:3], exec
	s_cselect_b32 s15, s21, s27
	s_cselect_b32 s51, s20, s26
	s_add_u32 s24, s24, 0x40080
	s_addc_u32 s25, s25, 0
	s_add_u32 s52, s26, 0x100
	s_addc_u32 s53, s27, 0
	s_mov_b32 s54, -2
	s_add_u32 s26, s24, 0xfffc0080
	s_addc_u32 s27, s25, -1
	s_add_i32 s55, 0, 0x10000
	s_cmp_eq_u32 s54, 12
	s_cselect_b32 s29, s17, s27
	s_cselect_b32 s28, s50, s26
	v_add_u32_e32 v140, s55, v143
	s_cselect_b32 s27, s15, s53
	s_cselect_b32 s26, s51, s52
	s_add_i32 s60, 0, 0x14000
	ds_read_b128 v[150:153], v140
	ds_read_b128 v[154:157], v140 offset:1024
	ds_read_b128 v[158:161], v140 offset:2048
	ds_read_b128 v[162:165], v140 offset:3072
	v_add_u32_e32 v140, s60, v143
	ds_read_b128 v[166:169], v140
	ds_read_b128 v[170:173], v140 offset:1024
	ds_read_b128 v[174:177], v140 offset:2048
	ds_read_b128 v[178:181], v140 offset:3072
	v_lshl_add_u64 v[140:141], s[24:25], 0, v[136:137]
	s_add_i32 m0, s40, 0xc000
	ds_read_b128 v[182:185], v148
	ds_read_b128 v[186:189], v148 offset:1024
	ds_read_b128 v[190:193], v148 offset:2048
	ds_read_b128 v[202:205], v148 offset:3072
	ds_read_b128 v[206:209], v148 offset:4096
	ds_read_b128 v[210:213], v148 offset:5120
	ds_read_b128 v[214:217], v148 offset:6144
	ds_read_b128 v[218:221], v148 offset:7168
	global_load_lds_dwordx4 v[140:141], off
	v_lshl_add_u64 v[140:141], s[24:25], 0, v[138:139]
	s_add_i32 m0, s40, 0xe000
	s_nop 0
	global_load_lds_dwordx4 v[140:141], off
	s_waitcnt lgkmcnt(0)
	s_barrier
	s_setprio 1
	s_waitcnt lgkmcnt(0)
	v_mfma_f32_16x16x32_bf16 v[126:129], v[150:153], v[182:185], 0
	v_mfma_f32_16x16x32_bf16 v[118:121], v[158:161], v[182:185], 0
	v_mfma_f32_16x16x32_bf16 v[110:113], v[150:153], v[190:193], 0
	v_mfma_f32_16x16x32_bf16 v[102:105], v[158:161], v[190:193], 0
	v_mfma_f32_16x16x32_bf16 v[92:95], v[150:153], v[206:209], 0
	v_mfma_f32_16x16x32_bf16 v[84:87], v[158:161], v[206:209], 0
	v_mfma_f32_16x16x32_bf16 v[76:79], v[150:153], v[214:217], 0
	v_mfma_f32_16x16x32_bf16 v[68:71], v[158:161], v[214:217], 0
	v_mfma_f32_16x16x32_bf16 v[126:129], v[154:157], v[186:189], v[126:129]
	v_mfma_f32_16x16x32_bf16 v[118:121], v[162:165], v[186:189], v[118:121]
	v_mfma_f32_16x16x32_bf16 v[110:113], v[154:157], v[202:205], v[110:113]
	v_mfma_f32_16x16x32_bf16 v[102:105], v[162:165], v[202:205], v[102:105]
	v_mfma_f32_16x16x32_bf16 v[92:95], v[154:157], v[210:213], v[92:95]
	v_mfma_f32_16x16x32_bf16 v[84:87], v[162:165], v[210:213], v[84:87]
	v_mfma_f32_16x16x32_bf16 v[76:79], v[154:157], v[218:221], v[76:79]
	v_mfma_f32_16x16x32_bf16 v[68:71], v[162:165], v[218:221], v[68:71]
	s_setprio 0
	s_setprio 1
	v_mfma_f32_16x16x32_bf16 v[122:125], v[166:169], v[182:185], 0
	v_mfma_f32_16x16x32_bf16 v[114:117], v[174:177], v[182:185], 0
	v_mfma_f32_16x16x32_bf16 v[106:109], v[166:169], v[190:193], 0
	v_mfma_f32_16x16x32_bf16 v[98:101], v[174:177], v[190:193], 0
	v_mfma_f32_16x16x32_bf16 v[88:91], v[166:169], v[206:209], 0
	v_mfma_f32_16x16x32_bf16 v[80:83], v[174:177], v[206:209], 0
	v_mfma_f32_16x16x32_bf16 v[72:75], v[166:169], v[214:217], 0
	v_mfma_f32_16x16x32_bf16 v[64:67], v[174:177], v[214:217], 0
	v_mfma_f32_16x16x32_bf16 v[122:125], v[170:173], v[186:189], v[122:125]
	v_mfma_f32_16x16x32_bf16 v[114:117], v[178:181], v[186:189], v[114:117]
	v_mfma_f32_16x16x32_bf16 v[106:109], v[170:173], v[202:205], v[106:109]
	v_mfma_f32_16x16x32_bf16 v[98:101], v[178:181], v[202:205], v[98:101]
	v_mfma_f32_16x16x32_bf16 v[88:91], v[170:173], v[210:213], v[88:91]
	v_mfma_f32_16x16x32_bf16 v[80:83], v[178:181], v[210:213], v[80:83]
	v_mfma_f32_16x16x32_bf16 v[72:75], v[170:173], v[218:221], v[72:75]
	v_mfma_f32_16x16x32_bf16 v[64:67], v[178:181], v[218:221], v[64:67]
	s_setprio 0
	s_barrier
	s_add_i32 s55, s55, s39
	v_lshl_add_u64 v[140:141], s[26:27], 0, v[96:97]
	s_mov_b32 m0, s55
	ds_read_b128 v[182:185], v148 offset:16384
	ds_read_b128 v[186:189], v148 offset:17408
	ds_read_b128 v[190:193], v148 offset:18432
	ds_read_b128 v[202:205], v148 offset:19456
	ds_read_b128 v[206:209], v148 offset:20480
	ds_read_b128 v[210:213], v148 offset:21504
	ds_read_b128 v[214:217], v148 offset:22528
	ds_read_b128 v[218:221], v148 offset:23552
	global_load_lds_dwordx4 v[140:141], off
	s_add_i32 m0, s55, 0x2000
	s_add_u32 s56, s26, 0x40000
	v_lshl_add_u64 v[194:195], s[26:27], 0, v[130:131]
	s_addc_u32 s57, s27, 0
	s_add_i32 s55, s60, s39
	global_load_lds_dwordx4 v[194:195], off
	v_lshl_add_u64 v[196:197], s[56:57], 0, v[96:97]
	s_mov_b32 m0, s55
	v_lshl_add_u64 v[198:199], s[28:29], 0, v[132:133]
	global_load_lds_dwordx4 v[196:197], off
	v_lshl_add_u64 v[196:197], s[56:57], 0, v[130:131]
	s_add_i32 m0, s55, 0x2000
	s_nop 0
	global_load_lds_dwordx4 v[196:197], off
	v_lshl_add_u64 v[196:197], s[28:29], 0, v[134:135]
	s_mov_b32 m0, s40
	s_nop 0
	global_load_lds_dwordx4 v[196:197], off
	s_mov_b32 m0, s41
	s_nop 0
	global_load_lds_dwordx4 v[198:199], off
	s_waitcnt lgkmcnt(0)
	s_barrier
	s_setprio 1
	s_waitcnt lgkmcnt(0)
	v_mfma_f32_16x16x32_bf16 v[60:63], v[150:153], v[182:185], 0
	v_mfma_f32_16x16x32_bf16 v[52:55], v[158:161], v[182:185], 0
	v_mfma_f32_16x16x32_bf16 v[44:47], v[150:153], v[190:193], 0
	v_mfma_f32_16x16x32_bf16 v[36:39], v[158:161], v[190:193], 0
	v_mfma_f32_16x16x32_bf16 v[28:31], v[150:153], v[206:209], 0
	v_mfma_f32_16x16x32_bf16 v[20:23], v[158:161], v[206:209], 0
	v_mfma_f32_16x16x32_bf16 v[12:15], v[150:153], v[214:217], 0
	v_mfma_f32_16x16x32_bf16 v[4:7], v[158:161], v[214:217], 0
	v_mfma_f32_16x16x32_bf16 v[60:63], v[154:157], v[186:189], v[60:63]
	v_mfma_f32_16x16x32_bf16 v[52:55], v[162:165], v[186:189], v[52:55]
	v_mfma_f32_16x16x32_bf16 v[44:47], v[154:157], v[202:205], v[44:47]
	v_mfma_f32_16x16x32_bf16 v[36:39], v[162:165], v[202:205], v[36:39]
	v_mfma_f32_16x16x32_bf16 v[28:31], v[154:157], v[210:213], v[28:31]
	v_mfma_f32_16x16x32_bf16 v[20:23], v[162:165], v[210:213], v[20:23]
	v_mfma_f32_16x16x32_bf16 v[12:15], v[154:157], v[218:221], v[12:15]
	v_mfma_f32_16x16x32_bf16 v[4:7], v[162:165], v[218:221], v[4:7]
	s_setprio 0
	s_setprio 1
	v_mfma_f32_16x16x32_bf16 v[56:59], v[166:169], v[182:185], 0
	v_mfma_f32_16x16x32_bf16 v[48:51], v[174:177], v[182:185], 0
	v_mfma_f32_16x16x32_bf16 v[40:43], v[166:169], v[190:193], 0
	v_mfma_f32_16x16x32_bf16 v[32:35], v[174:177], v[190:193], 0
	v_mfma_f32_16x16x32_bf16 v[24:27], v[166:169], v[206:209], 0
	v_mfma_f32_16x16x32_bf16 v[16:19], v[174:177], v[206:209], 0
	v_mfma_f32_16x16x32_bf16 v[8:11], v[166:169], v[214:217], 0
	v_mfma_f32_16x16x32_bf16 v[0:3], v[174:177], v[214:217], 0
	v_mfma_f32_16x16x32_bf16 v[56:59], v[170:173], v[186:189], v[56:59]
	v_mfma_f32_16x16x32_bf16 v[48:51], v[178:181], v[186:189], v[48:51]
	v_mfma_f32_16x16x32_bf16 v[40:43], v[170:173], v[202:205], v[40:43]
	v_mfma_f32_16x16x32_bf16 v[32:35], v[178:181], v[202:205], v[32:35]
	v_mfma_f32_16x16x32_bf16 v[24:27], v[170:173], v[210:213], v[24:27]
	v_mfma_f32_16x16x32_bf16 v[16:19], v[178:181], v[210:213], v[16:19]
	v_mfma_f32_16x16x32_bf16 v[8:11], v[170:173], v[218:221], v[8:11]
	v_mfma_f32_16x16x32_bf16 v[0:3], v[178:181], v[218:221], v[0:3]
	s_setprio 0
	s_barrier
	s_add_i32 s55, 0, 0x18000
	v_add_u32_e32 v149, s55, v143
	s_add_i32 s56, 0, 0x1c000
	ds_read_b128 v[150:153], v149
	ds_read_b128 v[154:157], v149 offset:1024
	ds_read_b128 v[158:161], v149 offset:2048
	ds_read_b128 v[162:165], v149 offset:3072
	v_add_u32_e32 v149, s56, v143
	ds_read_b128 v[166:169], v149
	ds_read_b128 v[170:173], v149 offset:1024
	ds_read_b128 v[174:177], v149 offset:2048
	ds_read_b128 v[178:181], v149 offset:3072
	s_add_u32 s28, s28, 0x40000
	s_addc_u32 s29, s29, 0
	s_mov_b32 m0, s42
	v_lshl_add_u64 v[200:201], s[28:29], 0, v[134:135]
	ds_read_b128 v[182:185], v148 offset:32768
	ds_read_b128 v[186:189], v148 offset:33792
	ds_read_b128 v[190:193], v148 offset:34816
	ds_read_b128 v[202:205], v148 offset:35840
	ds_read_b128 v[206:209], v148 offset:36864
	ds_read_b128 v[210:213], v148 offset:37888
	ds_read_b128 v[214:217], v148 offset:38912
	ds_read_b128 v[218:221], v148 offset:39936
	global_load_lds_dwordx4 v[200:201], off
	v_lshl_add_u64 v[200:201], s[28:29], 0, v[132:133]
	s_mov_b32 m0, s43
	s_nop 0
	global_load_lds_dwordx4 v[200:201], off
	s_waitcnt vmcnt(8)
	s_waitcnt lgkmcnt(0)
	s_barrier
	s_setprio 1
	s_waitcnt lgkmcnt(0)
	v_mfma_f32_16x16x32_bf16 v[126:129], v[150:153], v[182:185], v[126:129]
	v_mfma_f32_16x16x32_bf16 v[118:121], v[158:161], v[182:185], v[118:121]
	v_mfma_f32_16x16x32_bf16 v[110:113], v[150:153], v[190:193], v[110:113]
	v_mfma_f32_16x16x32_bf16 v[102:105], v[158:161], v[190:193], v[102:105]
	v_mfma_f32_16x16x32_bf16 v[92:95], v[150:153], v[206:209], v[92:95]
	v_mfma_f32_16x16x32_bf16 v[84:87], v[158:161], v[206:209], v[84:87]
	v_mfma_f32_16x16x32_bf16 v[76:79], v[150:153], v[214:217], v[76:79]
	v_mfma_f32_16x16x32_bf16 v[68:71], v[158:161], v[214:217], v[68:71]
	v_mfma_f32_16x16x32_bf16 v[126:129], v[154:157], v[186:189], v[126:129]
	v_mfma_f32_16x16x32_bf16 v[118:121], v[162:165], v[186:189], v[118:121]
	v_mfma_f32_16x16x32_bf16 v[110:113], v[154:157], v[202:205], v[110:113]
	v_mfma_f32_16x16x32_bf16 v[102:105], v[162:165], v[202:205], v[102:105]
	v_mfma_f32_16x16x32_bf16 v[92:95], v[154:157], v[210:213], v[92:95]
	v_mfma_f32_16x16x32_bf16 v[84:87], v[162:165], v[210:213], v[84:87]
	v_mfma_f32_16x16x32_bf16 v[76:79], v[154:157], v[218:221], v[76:79]
	v_mfma_f32_16x16x32_bf16 v[68:71], v[162:165], v[218:221], v[68:71]
	s_setprio 0
	s_setprio 1
	v_mfma_f32_16x16x32_bf16 v[122:125], v[166:169], v[182:185], v[122:125]
	v_mfma_f32_16x16x32_bf16 v[114:117], v[174:177], v[182:185], v[114:117]
	v_mfma_f32_16x16x32_bf16 v[106:109], v[166:169], v[190:193], v[106:109]
	v_mfma_f32_16x16x32_bf16 v[98:101], v[174:177], v[190:193], v[98:101]
	v_mfma_f32_16x16x32_bf16 v[88:91], v[166:169], v[206:209], v[88:91]
	v_mfma_f32_16x16x32_bf16 v[80:83], v[174:177], v[206:209], v[80:83]
	v_mfma_f32_16x16x32_bf16 v[72:75], v[166:169], v[214:217], v[72:75]
	v_mfma_f32_16x16x32_bf16 v[64:67], v[174:177], v[214:217], v[64:67]
	v_mfma_f32_16x16x32_bf16 v[122:125], v[170:173], v[186:189], v[122:125]
	v_mfma_f32_16x16x32_bf16 v[114:117], v[178:181], v[186:189], v[114:117]
	v_mfma_f32_16x16x32_bf16 v[106:109], v[170:173], v[202:205], v[106:109]
	v_mfma_f32_16x16x32_bf16 v[98:101], v[178:181], v[202:205], v[98:101]
	v_mfma_f32_16x16x32_bf16 v[88:91], v[170:173], v[210:213], v[88:91]
	v_mfma_f32_16x16x32_bf16 v[80:83], v[178:181], v[210:213], v[80:83]
	v_mfma_f32_16x16x32_bf16 v[72:75], v[170:173], v[218:221], v[72:75]
	v_mfma_f32_16x16x32_bf16 v[64:67], v[178:181], v[218:221], v[64:67]
	s_setprio 0
	s_barrier
	s_add_i32 s28, s55, s39
	v_lshl_add_u64 v[140:141], v[140:141], 0, s[64:65]
	s_mov_b32 m0, s28
	ds_read_b128 v[182:185], v148 offset:49152
	ds_read_b128 v[186:189], v148 offset:50176
	ds_read_b128 v[190:193], v148 offset:51200
	ds_read_b128 v[202:205], v148 offset:52224
	ds_read_b128 v[206:209], v148 offset:53248
	ds_read_b128 v[210:213], v148 offset:54272
	ds_read_b128 v[214:217], v148 offset:55296
	ds_read_b128 v[218:221], v148 offset:56320
	global_load_lds_dwordx4 v[140:141], off
	s_add_i32 m0, s28, 0x2000
	s_add_u32 s26, s26, 0x40080
	v_lshl_add_u64 v[140:141], v[194:195], 0, s[64:65]
	s_addc_u32 s27, s27, 0
	s_add_i32 s28, s56, s39
	global_load_lds_dwordx4 v[140:141], off
	v_lshl_add_u64 v[140:141], s[26:27], 0, v[96:97]
	s_mov_b32 m0, s28
	s_nop 0
	global_load_lds_dwordx4 v[140:141], off
	v_lshl_add_u64 v[140:141], s[26:27], 0, v[130:131]
	s_add_i32 m0, s28, 0x2000
	s_nop 0
	global_load_lds_dwordx4 v[140:141], off
	v_lshl_add_u64 v[140:141], v[196:197], 0, s[64:65]
	s_mov_b32 m0, s44
	s_nop 0
	global_load_lds_dwordx4 v[140:141], off
	v_lshl_add_u64 v[140:141], v[198:199], 0, s[64:65]
	s_mov_b32 m0, s45
	s_nop 0
	global_load_lds_dwordx4 v[140:141], off
	s_waitcnt vmcnt(8)
	s_waitcnt lgkmcnt(0)
	s_barrier
	s_setprio 1
	s_waitcnt lgkmcnt(0)
	v_mfma_f32_16x16x32_bf16 v[60:63], v[150:153], v[182:185], v[60:63]
	v_mfma_f32_16x16x32_bf16 v[52:55], v[158:161], v[182:185], v[52:55]
	v_mfma_f32_16x16x32_bf16 v[44:47], v[150:153], v[190:193], v[44:47]
	v_mfma_f32_16x16x32_bf16 v[36:39], v[158:161], v[190:193], v[36:39]
	v_mfma_f32_16x16x32_bf16 v[28:31], v[150:153], v[206:209], v[28:31]
	v_mfma_f32_16x16x32_bf16 v[20:23], v[158:161], v[206:209], v[20:23]
	v_mfma_f32_16x16x32_bf16 v[12:15], v[150:153], v[214:217], v[12:15]
	v_mfma_f32_16x16x32_bf16 v[4:7], v[158:161], v[214:217], v[4:7]
	v_mfma_f32_16x16x32_bf16 v[60:63], v[154:157], v[186:189], v[60:63]
	v_mfma_f32_16x16x32_bf16 v[52:55], v[162:165], v[186:189], v[52:55]
	v_mfma_f32_16x16x32_bf16 v[44:47], v[154:157], v[202:205], v[44:47]
	v_mfma_f32_16x16x32_bf16 v[36:39], v[162:165], v[202:205], v[36:39]
	v_mfma_f32_16x16x32_bf16 v[28:31], v[154:157], v[210:213], v[28:31]
	v_mfma_f32_16x16x32_bf16 v[20:23], v[162:165], v[210:213], v[20:23]
	v_mfma_f32_16x16x32_bf16 v[12:15], v[154:157], v[218:221], v[12:15]
	v_mfma_f32_16x16x32_bf16 v[4:7], v[162:165], v[218:221], v[4:7]
	s_setprio 0
	s_setprio 1
	v_mfma_f32_16x16x32_bf16 v[56:59], v[166:169], v[182:185], v[56:59]
	v_mfma_f32_16x16x32_bf16 v[48:51], v[174:177], v[182:185], v[48:51]
	v_mfma_f32_16x16x32_bf16 v[40:43], v[166:169], v[190:193], v[40:43]
	v_mfma_f32_16x16x32_bf16 v[32:35], v[174:177], v[190:193], v[32:35]
	v_mfma_f32_16x16x32_bf16 v[24:27], v[166:169], v[206:209], v[24:27]
	v_mfma_f32_16x16x32_bf16 v[16:19], v[174:177], v[206:209], v[16:19]
	v_mfma_f32_16x16x32_bf16 v[8:11], v[166:169], v[214:217], v[8:11]
	v_mfma_f32_16x16x32_bf16 v[0:3], v[174:177], v[214:217], v[0:3]
	v_mfma_f32_16x16x32_bf16 v[56:59], v[170:173], v[186:189], v[56:59]
	v_mfma_f32_16x16x32_bf16 v[48:51], v[178:181], v[186:189], v[48:51]
	v_mfma_f32_16x16x32_bf16 v[40:43], v[170:173], v[202:205], v[40:43]
	v_mfma_f32_16x16x32_bf16 v[32:35], v[178:181], v[202:205], v[32:35]
	v_mfma_f32_16x16x32_bf16 v[24:27], v[170:173], v[210:213], v[24:27]
	v_mfma_f32_16x16x32_bf16 v[16:19], v[178:181], v[210:213], v[16:19]
	v_mfma_f32_16x16x32_bf16 v[8:11], v[170:173], v[218:221], v[8:11]
	v_mfma_f32_16x16x32_bf16 v[0:3], v[178:181], v[218:221], v[0:3]
	s_setprio 0
	s_barrier
	s_add_i32 s54, s54, 2
	s_add_u32 s24, s24, 0x100
	s_addc_u32 s25, s25, 0
	s_add_u32 s52, s52, 0x100
	s_addc_u32 s53, s53, 0
	s_cmp_gt_u32 s54, 13
	s_cbranch_scc1 .Lgu_kdone
	.p2align 6

.LBB0_338:
	s_add_u32 s53, s28, 0x100
	s_addc_u32 s54, s29, 0
	s_mov_b32 s55, -2
	s_add_u32 s6, s26, 0x100
	s_addc_u32 s7, s27, 0
	s_add_i32 s56, 0, 0x10000
	s_cmp_eq_u32 s55, 40
	s_cselect_b32 s31, s23, s7
	s_cselect_b32 s30, s22, s6
	s_cselect_b32 s29, s25, s54
	s_cselect_b32 s28, s24, s53
	s_add_i32 s57, 0, 0x14000
	v_add_u32_e32 v106, s56, v254
	v_add_u32_e32 v150, s57, v254
	ds_read_b128 v[72:75], v106
	ds_read_b128 v[84:87], v106 offset:1024
	ds_read_b128 v[98:101], v106 offset:2048
	ds_read_b128 v[106:109], v106 offset:3072
	ds_read_b128 v[122:125], v150
	ds_read_b128 v[126:129], v150 offset:1024
	ds_read_b128 v[142:145], v150 offset:2048
	ds_read_b128 v[150:153], v150 offset:3072
	v_lshl_add_u64 v[194:195], s[26:27], 0, v[208:209]
	s_add_i32 m0, s40, 0xc000
	ds_read_b128 v[162:165], v198
	ds_read_b128 v[166:169], v198 offset:1024
	ds_read_b128 v[170:173], v198 offset:2048
	ds_read_b128 v[174:177], v198 offset:3072
	ds_read_b128 v[178:181], v198 offset:4096
	ds_read_b128 v[182:185], v198 offset:5120
	ds_read_b128 v[186:189], v198 offset:6144
	ds_read_b128 v[190:193], v198 offset:7168
	global_load_lds_dwordx4 v[194:195], off
	v_lshl_add_u64 v[194:195], s[26:27], 0, v[210:211]
	s_add_i32 m0, s40, 0xe000
	s_nop 0
	global_load_lds_dwordx4 v[194:195], off
	s_waitcnt vmcnt(8)
	s_waitcnt lgkmcnt(0)
	s_barrier
	s_setprio 1
	s_waitcnt lgkmcnt(0)
	v_mfma_f32_16x16x32_bf16 v[158:161], v[72:75], v[162:165], 0
	v_mfma_f32_16x16x32_bf16 v[154:157], v[98:101], v[162:165], 0
	v_mfma_f32_16x16x32_bf16 v[134:137], v[72:75], v[170:173], 0
	v_mfma_f32_16x16x32_bf16 v[130:133], v[98:101], v[170:173], 0
	v_mfma_f32_16x16x32_bf16 v[110:113], v[72:75], v[178:181], 0
	v_mfma_f32_16x16x32_bf16 v[102:105], v[98:101], v[178:181], 0
	v_mfma_f32_16x16x32_bf16 v[80:83], v[72:75], v[186:189], 0
	v_mfma_f32_16x16x32_bf16 v[76:79], v[98:101], v[186:189], 0
	v_mfma_f32_16x16x32_bf16 v[158:161], v[84:87], v[166:169], v[158:161]
	v_mfma_f32_16x16x32_bf16 v[154:157], v[106:109], v[166:169], v[154:157]
	v_mfma_f32_16x16x32_bf16 v[134:137], v[84:87], v[174:177], v[134:137]
	v_mfma_f32_16x16x32_bf16 v[130:133], v[106:109], v[174:177], v[130:133]
	v_mfma_f32_16x16x32_bf16 v[110:113], v[84:87], v[182:185], v[110:113]
	v_mfma_f32_16x16x32_bf16 v[102:105], v[106:109], v[182:185], v[102:105]
	v_mfma_f32_16x16x32_bf16 v[80:83], v[84:87], v[190:193], v[80:83]
	v_mfma_f32_16x16x32_bf16 v[76:79], v[106:109], v[190:193], v[76:79]
	s_setprio 0
	s_setprio 1
	v_mfma_f32_16x16x32_bf16 v[146:149], v[122:125], v[162:165], 0
	v_mfma_f32_16x16x32_bf16 v[138:141], v[142:145], v[162:165], 0
	v_mfma_f32_16x16x32_bf16 v[118:121], v[122:125], v[170:173], 0
	v_mfma_f32_16x16x32_bf16 v[114:117], v[142:145], v[170:173], 0
	v_mfma_f32_16x16x32_bf16 v[92:95], v[122:125], v[178:181], 0
	v_mfma_f32_16x16x32_bf16 v[88:91], v[142:145], v[178:181], 0
	v_mfma_f32_16x16x32_bf16 v[68:71], v[122:125], v[186:189], 0
	v_mfma_f32_16x16x32_bf16 v[64:67], v[142:145], v[186:189], 0
	v_mfma_f32_16x16x32_bf16 v[146:149], v[126:129], v[166:169], v[146:149]
	v_mfma_f32_16x16x32_bf16 v[138:141], v[150:153], v[166:169], v[138:141]
	v_mfma_f32_16x16x32_bf16 v[118:121], v[126:129], v[174:177], v[118:121]
	v_mfma_f32_16x16x32_bf16 v[114:117], v[150:153], v[174:177], v[114:117]
	v_mfma_f32_16x16x32_bf16 v[92:95], v[126:129], v[182:185], v[92:95]
	v_mfma_f32_16x16x32_bf16 v[88:91], v[150:153], v[182:185], v[88:91]
	v_mfma_f32_16x16x32_bf16 v[68:71], v[126:129], v[190:193], v[68:71]
	v_mfma_f32_16x16x32_bf16 v[64:67], v[150:153], v[190:193], v[64:67]
	s_setprio 0
	s_barrier
	s_add_i32 s26, s56, s39
	v_lshl_add_u64 v[194:195], s[28:29], 0, v[96:97]
	s_mov_b32 m0, s26
	ds_read_b128 v[162:165], v198 offset:16384
	ds_read_b128 v[166:169], v198 offset:17408
	ds_read_b128 v[170:173], v198 offset:18432
	ds_read_b128 v[174:177], v198 offset:19456
	ds_read_b128 v[178:181], v198 offset:20480
	ds_read_b128 v[182:185], v198 offset:21504
	ds_read_b128 v[186:189], v198 offset:22528
	ds_read_b128 v[190:193], v198 offset:23552
	global_load_lds_dwordx4 v[194:195], off
	s_add_i32 m0, s26, 0x2000
	s_add_u32 s26, s28, 0xb0000
	v_lshl_add_u64 v[196:197], s[28:29], 0, v[206:207]
	s_addc_u32 s27, s29, 0
	s_add_i32 s56, s57, s39
	global_load_lds_dwordx4 v[196:197], off
	v_lshl_add_u64 v[200:201], s[26:27], 0, v[96:97]
	s_mov_b32 m0, s56
	v_lshl_add_u64 v[212:213], s[30:31], 0, v[204:205]
	global_load_lds_dwordx4 v[200:201], off
	v_lshl_add_u64 v[200:201], s[26:27], 0, v[206:207]
	s_add_i32 m0, s56, 0x2000
	s_nop 0
	global_load_lds_dwordx4 v[200:201], off
	v_lshl_add_u64 v[200:201], s[30:31], 0, v[202:203]
	s_mov_b32 m0, s40
	s_nop 0
	global_load_lds_dwordx4 v[200:201], off
	s_mov_b32 m0, s41
	s_nop 0
	global_load_lds_dwordx4 v[212:213], off
	s_waitcnt vmcnt(8)
	s_waitcnt lgkmcnt(0)
	s_barrier
	s_setprio 1
	s_waitcnt lgkmcnt(0)
	v_mfma_f32_16x16x32_bf16 v[60:63], v[72:75], v[162:165], 0
	v_mfma_f32_16x16x32_bf16 v[56:59], v[98:101], v[162:165], 0
	v_mfma_f32_16x16x32_bf16 v[44:47], v[72:75], v[170:173], 0
	v_mfma_f32_16x16x32_bf16 v[40:43], v[98:101], v[170:173], 0
	v_mfma_f32_16x16x32_bf16 v[28:31], v[72:75], v[178:181], 0
	v_mfma_f32_16x16x32_bf16 v[24:27], v[98:101], v[178:181], 0
	v_mfma_f32_16x16x32_bf16 v[12:15], v[72:75], v[186:189], 0
	v_mfma_f32_16x16x32_bf16 v[8:11], v[98:101], v[186:189], 0
	v_mfma_f32_16x16x32_bf16 v[60:63], v[84:87], v[166:169], v[60:63]
	v_mfma_f32_16x16x32_bf16 v[56:59], v[106:109], v[166:169], v[56:59]
	v_mfma_f32_16x16x32_bf16 v[44:47], v[84:87], v[174:177], v[44:47]
	v_mfma_f32_16x16x32_bf16 v[40:43], v[106:109], v[174:177], v[40:43]
	v_mfma_f32_16x16x32_bf16 v[28:31], v[84:87], v[182:185], v[28:31]
	v_mfma_f32_16x16x32_bf16 v[24:27], v[106:109], v[182:185], v[24:27]
	v_mfma_f32_16x16x32_bf16 v[12:15], v[84:87], v[190:193], v[12:15]
	v_mfma_f32_16x16x32_bf16 v[8:11], v[106:109], v[190:193], v[8:11]
	s_setprio 0
	s_setprio 1
	v_mfma_f32_16x16x32_bf16 v[52:55], v[122:125], v[162:165], 0
	v_mfma_f32_16x16x32_bf16 v[48:51], v[142:145], v[162:165], 0
	v_mfma_f32_16x16x32_bf16 v[36:39], v[122:125], v[170:173], 0
	v_mfma_f32_16x16x32_bf16 v[32:35], v[142:145], v[170:173], 0
	v_mfma_f32_16x16x32_bf16 v[20:23], v[122:125], v[178:181], 0
	v_mfma_f32_16x16x32_bf16 v[16:19], v[142:145], v[178:181], 0
	v_mfma_f32_16x16x32_bf16 v[4:7], v[122:125], v[186:189], 0
	v_mfma_f32_16x16x32_bf16 v[0:3], v[142:145], v[186:189], 0
	v_mfma_f32_16x16x32_bf16 v[52:55], v[126:129], v[166:169], v[52:55]
	v_mfma_f32_16x16x32_bf16 v[48:51], v[150:153], v[166:169], v[48:51]
	v_mfma_f32_16x16x32_bf16 v[36:39], v[126:129], v[174:177], v[36:39]
	v_mfma_f32_16x16x32_bf16 v[32:35], v[150:153], v[174:177], v[32:35]
	v_mfma_f32_16x16x32_bf16 v[20:23], v[126:129], v[182:185], v[20:23]
	v_mfma_f32_16x16x32_bf16 v[16:19], v[150:153], v[182:185], v[16:19]
	v_mfma_f32_16x16x32_bf16 v[4:7], v[126:129], v[190:193], v[4:7]
	v_mfma_f32_16x16x32_bf16 v[0:3], v[150:153], v[190:193], v[0:3]
	s_setprio 0
	s_barrier
	s_add_i32 s56, 0, 0x18000
	s_add_i32 s57, 0, 0x1c000
	v_add_u32_e32 v106, s56, v254
	v_add_u32_e32 v150, s57, v254
	ds_read_b128 v[72:75], v106
	ds_read_b128 v[84:87], v106 offset:1024
	ds_read_b128 v[98:101], v106 offset:2048
	ds_read_b128 v[106:109], v106 offset:3072
	ds_read_b128 v[122:125], v150
	ds_read_b128 v[126:129], v150 offset:1024
	ds_read_b128 v[142:145], v150 offset:2048
	ds_read_b128 v[150:153], v150 offset:3072
	s_add_u32 s26, s30, 0xb0000
	s_addc_u32 s27, s31, 0
	s_mov_b32 m0, s42
	v_lshl_add_u64 v[214:215], s[26:27], 0, v[202:203]
	ds_read_b128 v[162:165], v198 offset:32768
	ds_read_b128 v[166:169], v198 offset:33792
	ds_read_b128 v[170:173], v198 offset:34816
	ds_read_b128 v[174:177], v198 offset:35840
	ds_read_b128 v[178:181], v198 offset:36864
	ds_read_b128 v[182:185], v198 offset:37888
	ds_read_b128 v[186:189], v198 offset:38912
	ds_read_b128 v[190:193], v198 offset:39936
	global_load_lds_dwordx4 v[214:215], off
	v_lshl_add_u64 v[214:215], s[26:27], 0, v[204:205]
	s_mov_b32 m0, s43
	s_nop 0
	global_load_lds_dwordx4 v[214:215], off
	s_waitcnt vmcnt(8)
	s_waitcnt lgkmcnt(0)
	s_barrier
	s_setprio 1
	s_waitcnt lgkmcnt(0)
	v_mfma_f32_16x16x32_bf16 v[158:161], v[72:75], v[162:165], v[158:161]
	v_mfma_f32_16x16x32_bf16 v[154:157], v[98:101], v[162:165], v[154:157]
	v_mfma_f32_16x16x32_bf16 v[134:137], v[72:75], v[170:173], v[134:137]
	v_mfma_f32_16x16x32_bf16 v[130:133], v[98:101], v[170:173], v[130:133]
	v_mfma_f32_16x16x32_bf16 v[110:113], v[72:75], v[178:181], v[110:113]
	v_mfma_f32_16x16x32_bf16 v[102:105], v[98:101], v[178:181], v[102:105]
	v_mfma_f32_16x16x32_bf16 v[80:83], v[72:75], v[186:189], v[80:83]
	v_mfma_f32_16x16x32_bf16 v[76:79], v[98:101], v[186:189], v[76:79]
	v_mfma_f32_16x16x32_bf16 v[158:161], v[84:87], v[166:169], v[158:161]
	v_mfma_f32_16x16x32_bf16 v[154:157], v[106:109], v[166:169], v[154:157]
	v_mfma_f32_16x16x32_bf16 v[134:137], v[84:87], v[174:177], v[134:137]
	v_mfma_f32_16x16x32_bf16 v[130:133], v[106:109], v[174:177], v[130:133]
	v_mfma_f32_16x16x32_bf16 v[110:113], v[84:87], v[182:185], v[110:113]
	v_mfma_f32_16x16x32_bf16 v[102:105], v[106:109], v[182:185], v[102:105]
	v_mfma_f32_16x16x32_bf16 v[80:83], v[84:87], v[190:193], v[80:83]
	v_mfma_f32_16x16x32_bf16 v[76:79], v[106:109], v[190:193], v[76:79]
	s_setprio 0
	s_setprio 1
	v_mfma_f32_16x16x32_bf16 v[146:149], v[122:125], v[162:165], v[146:149]
	v_mfma_f32_16x16x32_bf16 v[138:141], v[142:145], v[162:165], v[138:141]
	v_mfma_f32_16x16x32_bf16 v[118:121], v[122:125], v[170:173], v[118:121]
	v_mfma_f32_16x16x32_bf16 v[114:117], v[142:145], v[170:173], v[114:117]
	v_mfma_f32_16x16x32_bf16 v[92:95], v[122:125], v[178:181], v[92:95]
	v_mfma_f32_16x16x32_bf16 v[88:91], v[142:145], v[178:181], v[88:91]
	v_mfma_f32_16x16x32_bf16 v[68:71], v[122:125], v[186:189], v[68:71]
	v_mfma_f32_16x16x32_bf16 v[64:67], v[142:145], v[186:189], v[64:67]
	v_mfma_f32_16x16x32_bf16 v[146:149], v[126:129], v[166:169], v[146:149]
	v_mfma_f32_16x16x32_bf16 v[138:141], v[150:153], v[166:169], v[138:141]
	v_mfma_f32_16x16x32_bf16 v[118:121], v[126:129], v[174:177], v[118:121]
	v_mfma_f32_16x16x32_bf16 v[114:117], v[150:153], v[174:177], v[114:117]
	v_mfma_f32_16x16x32_bf16 v[92:95], v[126:129], v[182:185], v[92:95]
	v_mfma_f32_16x16x32_bf16 v[88:91], v[150:153], v[182:185], v[88:91]
	v_mfma_f32_16x16x32_bf16 v[68:71], v[126:129], v[190:193], v[68:71]
	v_mfma_f32_16x16x32_bf16 v[64:67], v[150:153], v[190:193], v[64:67]
	s_setprio 0
	s_barrier
	s_add_i32 s26, s56, s39
	v_lshl_add_u64 v[194:195], v[194:195], 0, s[64:65]
	s_mov_b32 m0, s26
	ds_read_b128 v[162:165], v198 offset:49152
	ds_read_b128 v[166:169], v198 offset:50176
	ds_read_b128 v[170:173], v198 offset:51200
	ds_read_b128 v[174:177], v198 offset:52224
	ds_read_b128 v[178:181], v198 offset:53248
	ds_read_b128 v[182:185], v198 offset:54272
	ds_read_b128 v[186:189], v198 offset:55296
	ds_read_b128 v[190:193], v198 offset:56320
	global_load_lds_dwordx4 v[194:195], off
	s_add_i32 m0, s26, 0x2000
	s_add_u32 s26, s28, 0xb0080
	v_lshl_add_u64 v[194:195], v[196:197], 0, s[64:65]
	s_addc_u32 s27, s29, 0
	s_add_i32 s28, s57, s39
	global_load_lds_dwordx4 v[194:195], off
	v_lshl_add_u64 v[194:195], s[26:27], 0, v[96:97]
	s_mov_b32 m0, s28
	s_nop 0
	global_load_lds_dwordx4 v[194:195], off
	v_lshl_add_u64 v[194:195], s[26:27], 0, v[206:207]
	s_add_i32 m0, s28, 0x2000
	s_nop 0
	global_load_lds_dwordx4 v[194:195], off
	v_lshl_add_u64 v[194:195], v[200:201], 0, s[64:65]
	s_mov_b32 m0, s45
	s_nop 0
	global_load_lds_dwordx4 v[194:195], off
	v_lshl_add_u64 v[194:195], v[212:213], 0, s[64:65]
	s_mov_b32 m0, s46
	s_nop 0
	global_load_lds_dwordx4 v[194:195], off
	s_waitcnt vmcnt(8)
	s_waitcnt lgkmcnt(0)
	s_barrier
	s_setprio 1
	s_waitcnt lgkmcnt(0)
	v_mfma_f32_16x16x32_bf16 v[60:63], v[72:75], v[162:165], v[60:63]
	v_mfma_f32_16x16x32_bf16 v[56:59], v[98:101], v[162:165], v[56:59]
	v_mfma_f32_16x16x32_bf16 v[44:47], v[72:75], v[170:173], v[44:47]
	v_mfma_f32_16x16x32_bf16 v[40:43], v[98:101], v[170:173], v[40:43]
	v_mfma_f32_16x16x32_bf16 v[28:31], v[72:75], v[178:181], v[28:31]
	v_mfma_f32_16x16x32_bf16 v[24:27], v[98:101], v[178:181], v[24:27]
	v_mfma_f32_16x16x32_bf16 v[12:15], v[72:75], v[186:189], v[12:15]
	v_mfma_f32_16x16x32_bf16 v[8:11], v[98:101], v[186:189], v[8:11]
	v_mfma_f32_16x16x32_bf16 v[60:63], v[84:87], v[166:169], v[60:63]
	v_mfma_f32_16x16x32_bf16 v[56:59], v[106:109], v[166:169], v[56:59]
	v_mfma_f32_16x16x32_bf16 v[44:47], v[84:87], v[174:177], v[44:47]
	v_mfma_f32_16x16x32_bf16 v[40:43], v[106:109], v[174:177], v[40:43]
	v_mfma_f32_16x16x32_bf16 v[28:31], v[84:87], v[182:185], v[28:31]
	v_mfma_f32_16x16x32_bf16 v[24:27], v[106:109], v[182:185], v[24:27]
	v_mfma_f32_16x16x32_bf16 v[12:15], v[84:87], v[190:193], v[12:15]
	v_mfma_f32_16x16x32_bf16 v[8:11], v[106:109], v[190:193], v[8:11]
	s_setprio 0
	s_setprio 1
	v_mfma_f32_16x16x32_bf16 v[52:55], v[122:125], v[162:165], v[52:55]
	v_mfma_f32_16x16x32_bf16 v[48:51], v[142:145], v[162:165], v[48:51]
	v_mfma_f32_16x16x32_bf16 v[36:39], v[122:125], v[170:173], v[36:39]
	v_mfma_f32_16x16x32_bf16 v[32:35], v[142:145], v[170:173], v[32:35]
	v_mfma_f32_16x16x32_bf16 v[20:23], v[122:125], v[178:181], v[20:23]
	v_mfma_f32_16x16x32_bf16 v[16:19], v[142:145], v[178:181], v[16:19]
	v_mfma_f32_16x16x32_bf16 v[4:7], v[122:125], v[186:189], v[4:7]
	v_mfma_f32_16x16x32_bf16 v[0:3], v[142:145], v[186:189], v[0:3]
	v_mfma_f32_16x16x32_bf16 v[52:55], v[126:129], v[166:169], v[52:55]
	v_mfma_f32_16x16x32_bf16 v[48:51], v[150:153], v[166:169], v[48:51]
	v_mfma_f32_16x16x32_bf16 v[36:39], v[126:129], v[174:177], v[36:39]
	v_mfma_f32_16x16x32_bf16 v[32:35], v[150:153], v[174:177], v[32:35]
	v_mfma_f32_16x16x32_bf16 v[20:23], v[126:129], v[182:185], v[20:23]
	v_mfma_f32_16x16x32_bf16 v[16:19], v[150:153], v[182:185], v[16:19]
	v_mfma_f32_16x16x32_bf16 v[4:7], v[126:129], v[190:193], v[4:7]
	v_mfma_f32_16x16x32_bf16 v[0:3], v[150:153], v[190:193], v[0:3]
	s_setprio 0
	s_barrier
	s_add_i32 s55, s55, 2
	s_add_u32 s53, s53, 0x100
	s_addc_u32 s54, s54, 0
	s_cmp_gt_u32 s55, 41
	s_mov_b64 s[26:27], s[6:7]
	s_cbranch_scc1 .Lpeel_done_339
	.p2align 6

.LBB0_460:
	s_ashr_i32 s21, s20, 31
	s_lshl_b64 s[22:23], s[20:21], 19
	s_add_u32 s22, s40, s22
	s_addc_u32 s23, s41, s23
	s_and_b64 s[24:25], s[2:3], exec
	s_cselect_b32 s21, s23, s29
	s_cselect_b32 s51, s22, s28
	s_ashr_i32 s19, s18, 31
	s_lshl_b64 s[24:25], s[18:19], 19
	s_add_u32 s24, s38, s24
	s_addc_u32 s25, s39, s25
	s_and_b64 s[34:35], s[2:3], exec
	s_cselect_b32 s19, s25, s31
	s_cselect_b32 s52, s24, s30
	s_add_u32 s28, s28, 0x40080
	s_addc_u32 s29, s29, 0
	s_add_u32 s53, s30, 0x100
	s_addc_u32 s54, s31, 0
	s_mov_b32 s55, -2
	s_add_u32 s30, s28, 0xfffc0080
	s_addc_u32 s31, s29, -1
	s_add_i32 s56, 0, 0x10000
	s_cmp_eq_u32 s55, 12
	s_cselect_b32 s35, s21, s31
	s_cselect_b32 s34, s51, s30
	v_add_u32_e32 v96, s56, v148
	s_cselect_b32 s31, s19, s54
	s_cselect_b32 s30, s52, s53
	s_add_i32 s60, 0, 0x14000
	ds_read_b128 v[144:147], v96
	ds_read_b128 v[154:157], v96 offset:1024
	ds_read_b128 v[158:161], v96 offset:2048
	ds_read_b128 v[162:165], v96 offset:3072
	v_add_u32_e32 v96, s60, v148
	ds_read_b128 v[166:169], v96
	ds_read_b128 v[170:173], v96 offset:1024
	ds_read_b128 v[174:177], v96 offset:2048
	ds_read_b128 v[178:181], v96 offset:3072
	v_lshl_add_u64 v[214:215], s[28:29], 0, v[140:141]
	s_add_i32 m0, s43, 0xc000
	ds_read_b128 v[182:185], v152
	ds_read_b128 v[186:189], v152 offset:1024
	ds_read_b128 v[190:193], v152 offset:2048
	ds_read_b128 v[194:197], v152 offset:3072
	ds_read_b128 v[198:201], v152 offset:4096
	ds_read_b128 v[202:205], v152 offset:5120
	ds_read_b128 v[206:209], v152 offset:6144
	ds_read_b128 v[210:213], v152 offset:7168
	global_load_lds_dwordx4 v[214:215], off
	v_lshl_add_u64 v[214:215], s[28:29], 0, v[142:143]
	s_add_i32 m0, s43, 0xe000
	s_nop 0
	global_load_lds_dwordx4 v[214:215], off
	s_waitcnt vmcnt(8)
	s_waitcnt lgkmcnt(0)
	s_barrier
	s_setprio 1
	s_waitcnt lgkmcnt(0)
	v_mfma_f32_16x16x32_bf16 v[122:125], v[144:147], v[182:185], 0
	v_mfma_f32_16x16x32_bf16 v[126:129], v[158:161], v[182:185], 0
	v_mfma_f32_16x16x32_bf16 v[106:109], v[144:147], v[190:193], 0
	v_mfma_f32_16x16x32_bf16 v[110:113], v[158:161], v[190:193], 0
	v_mfma_f32_16x16x32_bf16 v[88:91], v[144:147], v[198:201], 0
	v_mfma_f32_16x16x32_bf16 v[92:95], v[158:161], v[198:201], 0
	v_mfma_f32_16x16x32_bf16 v[72:75], v[144:147], v[206:209], 0
	v_mfma_f32_16x16x32_bf16 v[76:79], v[158:161], v[206:209], 0
	v_mfma_f32_16x16x32_bf16 v[122:125], v[154:157], v[186:189], v[122:125]
	v_mfma_f32_16x16x32_bf16 v[126:129], v[162:165], v[186:189], v[126:129]
	v_mfma_f32_16x16x32_bf16 v[106:109], v[154:157], v[194:197], v[106:109]
	v_mfma_f32_16x16x32_bf16 v[110:113], v[162:165], v[194:197], v[110:113]
	v_mfma_f32_16x16x32_bf16 v[88:91], v[154:157], v[202:205], v[88:91]
	v_mfma_f32_16x16x32_bf16 v[92:95], v[162:165], v[202:205], v[92:95]
	v_mfma_f32_16x16x32_bf16 v[72:75], v[154:157], v[210:213], v[72:75]
	v_mfma_f32_16x16x32_bf16 v[76:79], v[162:165], v[210:213], v[76:79]
	s_setprio 0
	s_setprio 1
	v_mfma_f32_16x16x32_bf16 v[118:121], v[166:169], v[182:185], 0
	v_mfma_f32_16x16x32_bf16 v[114:117], v[174:177], v[182:185], 0
	v_mfma_f32_16x16x32_bf16 v[102:105], v[166:169], v[190:193], 0
	v_mfma_f32_16x16x32_bf16 v[98:101], v[174:177], v[190:193], 0
	v_mfma_f32_16x16x32_bf16 v[84:87], v[166:169], v[198:201], 0
	v_mfma_f32_16x16x32_bf16 v[80:83], v[174:177], v[198:201], 0
	v_mfma_f32_16x16x32_bf16 v[68:71], v[166:169], v[206:209], 0
	v_mfma_f32_16x16x32_bf16 v[64:67], v[174:177], v[206:209], 0
	v_mfma_f32_16x16x32_bf16 v[118:121], v[170:173], v[186:189], v[118:121]
	v_mfma_f32_16x16x32_bf16 v[114:117], v[178:181], v[186:189], v[114:117]
	v_mfma_f32_16x16x32_bf16 v[102:105], v[170:173], v[194:197], v[102:105]
	v_mfma_f32_16x16x32_bf16 v[98:101], v[178:181], v[194:197], v[98:101]
	v_mfma_f32_16x16x32_bf16 v[84:87], v[170:173], v[202:205], v[84:87]
	v_mfma_f32_16x16x32_bf16 v[80:83], v[178:181], v[202:205], v[80:83]
	v_mfma_f32_16x16x32_bf16 v[68:71], v[170:173], v[210:213], v[68:71]
	v_mfma_f32_16x16x32_bf16 v[64:67], v[178:181], v[210:213], v[64:67]
	s_setprio 0
	s_barrier
	s_add_i32 s56, s56, s42
	v_lshl_add_u64 v[214:215], s[30:31], 0, v[132:133]
	s_mov_b32 m0, s56
	ds_read_b128 v[182:185], v152 offset:16384
	ds_read_b128 v[186:189], v152 offset:17408
	ds_read_b128 v[190:193], v152 offset:18432
	ds_read_b128 v[194:197], v152 offset:19456
	ds_read_b128 v[198:201], v152 offset:20480
	ds_read_b128 v[202:205], v152 offset:21504
	ds_read_b128 v[206:209], v152 offset:22528
	ds_read_b128 v[210:213], v152 offset:23552
	global_load_lds_dwordx4 v[214:215], off
	s_add_i32 m0, s56, 0x2000
	s_add_u32 s56, s30, 0x40000
	v_lshl_add_u64 v[216:217], s[30:31], 0, v[136:137]
	s_addc_u32 s57, s31, 0
	s_add_i32 s60, s60, s42
	global_load_lds_dwordx4 v[216:217], off
	v_lshl_add_u64 v[218:219], s[56:57], 0, v[132:133]
	s_mov_b32 m0, s60
	v_lshl_add_u64 v[220:221], s[34:35], 0, v[134:135]
	global_load_lds_dwordx4 v[218:219], off
	v_lshl_add_u64 v[218:219], s[56:57], 0, v[136:137]
	s_add_i32 m0, s60, 0x2000
	s_nop 0
	global_load_lds_dwordx4 v[218:219], off
	v_lshl_add_u64 v[218:219], s[34:35], 0, v[130:131]
	s_mov_b32 m0, s43
	s_nop 0
	global_load_lds_dwordx4 v[218:219], off
	s_mov_b32 m0, s44
	s_nop 0
	global_load_lds_dwordx4 v[220:221], off
	s_waitcnt vmcnt(8)
	s_waitcnt lgkmcnt(0)
	s_barrier
	s_setprio 1
	s_waitcnt lgkmcnt(0)
	v_mfma_f32_16x16x32_bf16 v[56:59], v[144:147], v[182:185], 0
	v_mfma_f32_16x16x32_bf16 v[60:63], v[158:161], v[182:185], 0
	v_mfma_f32_16x16x32_bf16 v[40:43], v[144:147], v[190:193], 0
	v_mfma_f32_16x16x32_bf16 v[44:47], v[158:161], v[190:193], 0
	v_mfma_f32_16x16x32_bf16 v[24:27], v[144:147], v[198:201], 0
	v_mfma_f32_16x16x32_bf16 v[28:31], v[158:161], v[198:201], 0
	v_mfma_f32_16x16x32_bf16 v[8:11], v[144:147], v[206:209], 0
	v_mfma_f32_16x16x32_bf16 v[12:15], v[158:161], v[206:209], 0
	v_mfma_f32_16x16x32_bf16 v[56:59], v[154:157], v[186:189], v[56:59]
	v_mfma_f32_16x16x32_bf16 v[60:63], v[162:165], v[186:189], v[60:63]
	v_mfma_f32_16x16x32_bf16 v[40:43], v[154:157], v[194:197], v[40:43]
	v_mfma_f32_16x16x32_bf16 v[44:47], v[162:165], v[194:197], v[44:47]
	v_mfma_f32_16x16x32_bf16 v[24:27], v[154:157], v[202:205], v[24:27]
	v_mfma_f32_16x16x32_bf16 v[28:31], v[162:165], v[202:205], v[28:31]
	v_mfma_f32_16x16x32_bf16 v[8:11], v[154:157], v[210:213], v[8:11]
	v_mfma_f32_16x16x32_bf16 v[12:15], v[162:165], v[210:213], v[12:15]
	s_setprio 0
	s_setprio 1
	v_mfma_f32_16x16x32_bf16 v[52:55], v[166:169], v[182:185], 0
	v_mfma_f32_16x16x32_bf16 v[48:51], v[174:177], v[182:185], 0
	v_mfma_f32_16x16x32_bf16 v[36:39], v[166:169], v[190:193], 0
	v_mfma_f32_16x16x32_bf16 v[32:35], v[174:177], v[190:193], 0
	v_mfma_f32_16x16x32_bf16 v[20:23], v[166:169], v[198:201], 0
	v_mfma_f32_16x16x32_bf16 v[16:19], v[174:177], v[198:201], 0
	v_mfma_f32_16x16x32_bf16 v[4:7], v[166:169], v[206:209], 0
	v_mfma_f32_16x16x32_bf16 v[0:3], v[174:177], v[206:209], 0
	v_mfma_f32_16x16x32_bf16 v[52:55], v[170:173], v[186:189], v[52:55]
	v_mfma_f32_16x16x32_bf16 v[48:51], v[178:181], v[186:189], v[48:51]
	v_mfma_f32_16x16x32_bf16 v[36:39], v[170:173], v[194:197], v[36:39]
	v_mfma_f32_16x16x32_bf16 v[32:35], v[178:181], v[194:197], v[32:35]
	v_mfma_f32_16x16x32_bf16 v[20:23], v[170:173], v[202:205], v[20:23]
	v_mfma_f32_16x16x32_bf16 v[16:19], v[178:181], v[202:205], v[16:19]
	v_mfma_f32_16x16x32_bf16 v[4:7], v[170:173], v[210:213], v[4:7]
	v_mfma_f32_16x16x32_bf16 v[0:3], v[178:181], v[210:213], v[0:3]
	s_setprio 0
	s_barrier
	s_add_i32 s56, 0, 0x18000
	v_add_u32_e32 v96, s56, v148
	s_add_i32 s57, 0, 0x1c000
	ds_read_b128 v[144:147], v96
	ds_read_b128 v[154:157], v96 offset:1024
	ds_read_b128 v[158:161], v96 offset:2048
	ds_read_b128 v[162:165], v96 offset:3072
	v_add_u32_e32 v96, s57, v148
	ds_read_b128 v[166:169], v96
	ds_read_b128 v[170:173], v96 offset:1024
	ds_read_b128 v[174:177], v96 offset:2048
	ds_read_b128 v[178:181], v96 offset:3072
	s_add_u32 s34, s34, 0x40000
	s_addc_u32 s35, s35, 0
	s_mov_b32 m0, s45
	v_lshl_add_u64 v[222:223], s[34:35], 0, v[130:131]
	ds_read_b128 v[182:185], v152 offset:32768
	ds_read_b128 v[186:189], v152 offset:33792
	ds_read_b128 v[190:193], v152 offset:34816
	ds_read_b128 v[194:197], v152 offset:35840
	ds_read_b128 v[198:201], v152 offset:36864
	ds_read_b128 v[202:205], v152 offset:37888
	ds_read_b128 v[206:209], v152 offset:38912
	ds_read_b128 v[210:213], v152 offset:39936
	global_load_lds_dwordx4 v[222:223], off
	v_lshl_add_u64 v[222:223], s[34:35], 0, v[134:135]
	s_mov_b32 m0, s46
	s_nop 0
	global_load_lds_dwordx4 v[222:223], off
	s_waitcnt vmcnt(8)
	s_waitcnt lgkmcnt(0)
	s_barrier
	s_setprio 1
	s_waitcnt lgkmcnt(0)
	v_mfma_f32_16x16x32_bf16 v[122:125], v[144:147], v[182:185], v[122:125]
	v_mfma_f32_16x16x32_bf16 v[126:129], v[158:161], v[182:185], v[126:129]
	v_mfma_f32_16x16x32_bf16 v[106:109], v[144:147], v[190:193], v[106:109]
	v_mfma_f32_16x16x32_bf16 v[110:113], v[158:161], v[190:193], v[110:113]
	v_mfma_f32_16x16x32_bf16 v[88:91], v[144:147], v[198:201], v[88:91]
	v_mfma_f32_16x16x32_bf16 v[92:95], v[158:161], v[198:201], v[92:95]
	v_mfma_f32_16x16x32_bf16 v[72:75], v[144:147], v[206:209], v[72:75]
	v_mfma_f32_16x16x32_bf16 v[76:79], v[158:161], v[206:209], v[76:79]
	v_mfma_f32_16x16x32_bf16 v[122:125], v[154:157], v[186:189], v[122:125]
	v_mfma_f32_16x16x32_bf16 v[126:129], v[162:165], v[186:189], v[126:129]
	v_mfma_f32_16x16x32_bf16 v[106:109], v[154:157], v[194:197], v[106:109]
	v_mfma_f32_16x16x32_bf16 v[110:113], v[162:165], v[194:197], v[110:113]
	v_mfma_f32_16x16x32_bf16 v[88:91], v[154:157], v[202:205], v[88:91]
	v_mfma_f32_16x16x32_bf16 v[92:95], v[162:165], v[202:205], v[92:95]
	v_mfma_f32_16x16x32_bf16 v[72:75], v[154:157], v[210:213], v[72:75]
	v_mfma_f32_16x16x32_bf16 v[76:79], v[162:165], v[210:213], v[76:79]
	s_setprio 0
	s_setprio 1
	v_mfma_f32_16x16x32_bf16 v[118:121], v[166:169], v[182:185], v[118:121]
	v_mfma_f32_16x16x32_bf16 v[114:117], v[174:177], v[182:185], v[114:117]
	v_mfma_f32_16x16x32_bf16 v[102:105], v[166:169], v[190:193], v[102:105]
	v_mfma_f32_16x16x32_bf16 v[98:101], v[174:177], v[190:193], v[98:101]
	v_mfma_f32_16x16x32_bf16 v[84:87], v[166:169], v[198:201], v[84:87]
	v_mfma_f32_16x16x32_bf16 v[80:83], v[174:177], v[198:201], v[80:83]
	v_mfma_f32_16x16x32_bf16 v[68:71], v[166:169], v[206:209], v[68:71]
	v_mfma_f32_16x16x32_bf16 v[64:67], v[174:177], v[206:209], v[64:67]
	v_mfma_f32_16x16x32_bf16 v[118:121], v[170:173], v[186:189], v[118:121]
	v_mfma_f32_16x16x32_bf16 v[114:117], v[178:181], v[186:189], v[114:117]
	v_mfma_f32_16x16x32_bf16 v[102:105], v[170:173], v[194:197], v[102:105]
	v_mfma_f32_16x16x32_bf16 v[98:101], v[178:181], v[194:197], v[98:101]
	v_mfma_f32_16x16x32_bf16 v[84:87], v[170:173], v[202:205], v[84:87]
	v_mfma_f32_16x16x32_bf16 v[80:83], v[178:181], v[202:205], v[80:83]
	v_mfma_f32_16x16x32_bf16 v[68:71], v[170:173], v[210:213], v[68:71]
	v_mfma_f32_16x16x32_bf16 v[64:67], v[178:181], v[210:213], v[64:67]
	s_setprio 0
	s_barrier
	s_add_i32 s34, s56, s42
	v_lshl_add_u64 v[214:215], v[214:215], 0, s[64:65]
	s_mov_b32 m0, s34
	ds_read_b128 v[182:185], v152 offset:49152
	ds_read_b128 v[186:189], v152 offset:50176
	ds_read_b128 v[190:193], v152 offset:51200
	ds_read_b128 v[194:197], v152 offset:52224
	ds_read_b128 v[198:201], v152 offset:53248
	ds_read_b128 v[202:205], v152 offset:54272
	ds_read_b128 v[206:209], v152 offset:55296
	ds_read_b128 v[210:213], v152 offset:56320
	global_load_lds_dwordx4 v[214:215], off
	s_add_i32 m0, s34, 0x2000
	s_add_u32 s30, s30, 0x40080
	v_lshl_add_u64 v[214:215], v[216:217], 0, s[64:65]
	s_addc_u32 s31, s31, 0
	s_add_i32 s34, s57, s42
	global_load_lds_dwordx4 v[214:215], off
	v_lshl_add_u64 v[214:215], s[30:31], 0, v[132:133]
	s_mov_b32 m0, s34
	s_nop 0
	global_load_lds_dwordx4 v[214:215], off
	v_lshl_add_u64 v[214:215], s[30:31], 0, v[136:137]
	s_add_i32 m0, s34, 0x2000
	s_nop 0
	global_load_lds_dwordx4 v[214:215], off
	v_lshl_add_u64 v[214:215], v[218:219], 0, s[64:65]
	s_mov_b32 m0, s48
	s_nop 0
	global_load_lds_dwordx4 v[214:215], off
	v_lshl_add_u64 v[214:215], v[220:221], 0, s[64:65]
	s_mov_b32 m0, s49
	s_nop 0
	global_load_lds_dwordx4 v[214:215], off
	s_waitcnt vmcnt(8)
	s_waitcnt lgkmcnt(0)
	s_barrier
	s_setprio 1
	s_waitcnt lgkmcnt(0)
	v_mfma_f32_16x16x32_bf16 v[56:59], v[144:147], v[182:185], v[56:59]
	v_mfma_f32_16x16x32_bf16 v[60:63], v[158:161], v[182:185], v[60:63]
	v_mfma_f32_16x16x32_bf16 v[40:43], v[144:147], v[190:193], v[40:43]
	v_mfma_f32_16x16x32_bf16 v[44:47], v[158:161], v[190:193], v[44:47]
	v_mfma_f32_16x16x32_bf16 v[24:27], v[144:147], v[198:201], v[24:27]
	v_mfma_f32_16x16x32_bf16 v[28:31], v[158:161], v[198:201], v[28:31]
	v_mfma_f32_16x16x32_bf16 v[8:11], v[144:147], v[206:209], v[8:11]
	v_mfma_f32_16x16x32_bf16 v[12:15], v[158:161], v[206:209], v[12:15]
	v_mfma_f32_16x16x32_bf16 v[56:59], v[154:157], v[186:189], v[56:59]
	v_mfma_f32_16x16x32_bf16 v[60:63], v[162:165], v[186:189], v[60:63]
	v_mfma_f32_16x16x32_bf16 v[40:43], v[154:157], v[194:197], v[40:43]
	v_mfma_f32_16x16x32_bf16 v[44:47], v[162:165], v[194:197], v[44:47]
	v_mfma_f32_16x16x32_bf16 v[24:27], v[154:157], v[202:205], v[24:27]
	v_mfma_f32_16x16x32_bf16 v[28:31], v[162:165], v[202:205], v[28:31]
	v_mfma_f32_16x16x32_bf16 v[8:11], v[154:157], v[210:213], v[8:11]
	v_mfma_f32_16x16x32_bf16 v[12:15], v[162:165], v[210:213], v[12:15]
	s_setprio 0
	s_setprio 1
	v_mfma_f32_16x16x32_bf16 v[52:55], v[166:169], v[182:185], v[52:55]
	v_mfma_f32_16x16x32_bf16 v[48:51], v[174:177], v[182:185], v[48:51]
	v_mfma_f32_16x16x32_bf16 v[36:39], v[166:169], v[190:193], v[36:39]
	v_mfma_f32_16x16x32_bf16 v[32:35], v[174:177], v[190:193], v[32:35]
	v_mfma_f32_16x16x32_bf16 v[20:23], v[166:169], v[198:201], v[20:23]
	v_mfma_f32_16x16x32_bf16 v[16:19], v[174:177], v[198:201], v[16:19]
	v_mfma_f32_16x16x32_bf16 v[4:7], v[166:169], v[206:209], v[4:7]
	v_mfma_f32_16x16x32_bf16 v[0:3], v[174:177], v[206:209], v[0:3]
	v_mfma_f32_16x16x32_bf16 v[52:55], v[170:173], v[186:189], v[52:55]
	v_mfma_f32_16x16x32_bf16 v[48:51], v[178:181], v[186:189], v[48:51]
	v_mfma_f32_16x16x32_bf16 v[36:39], v[170:173], v[194:197], v[36:39]
	v_mfma_f32_16x16x32_bf16 v[32:35], v[178:181], v[194:197], v[32:35]
	v_mfma_f32_16x16x32_bf16 v[20:23], v[170:173], v[202:205], v[20:23]
	v_mfma_f32_16x16x32_bf16 v[16:19], v[178:181], v[202:205], v[16:19]
	v_mfma_f32_16x16x32_bf16 v[4:7], v[170:173], v[210:213], v[4:7]
	v_mfma_f32_16x16x32_bf16 v[0:3], v[178:181], v[210:213], v[0:3]
	s_setprio 0
	s_barrier
	s_add_i32 s55, s55, 2
	s_add_u32 s28, s28, 0x100
	s_addc_u32 s29, s29, 0
	s_add_u32 s53, s53, 0x100
	s_addc_u32 s54, s54, 0
	s_cmp_gt_u32 s55, 13
	s_cbranch_scc1 .Lpeel_done_461
	.p2align 6

.LBB0_633:
	s_ashr_i32 s17, s16, 31
	s_lshl_b64 s[18:19], s[16:17], 19
	s_add_u32 s18, s35, s18
	s_addc_u32 s19, s36, s19
	s_and_b64 s[20:21], s[4:5], exec
	s_cselect_b32 s17, s19, s27
	s_cselect_b32 s23, s18, s26
	s_ashr_i32 s15, s14, 31
	s_lshl_b64 s[20:21], s[14:15], 19
	s_add_u32 s20, s37, s20
	s_addc_u32 s21, s38, s21
	s_and_b64 s[30:31], s[4:5], exec
	s_cselect_b32 s15, s21, s29
	s_cselect_b32 s25, s20, s28
	s_add_u32 s26, s26, 0x40080
	s_addc_u32 s27, s27, 0
	s_add_u32 s49, s28, 0x100
	s_addc_u32 s50, s29, 0
	s_mov_b32 s51, -2
	s_add_u32 s28, s26, 0xfffc0080
	s_addc_u32 s29, s27, -1
	s_add_i32 s52, 0, 0x10000
	s_cmp_eq_u32 s51, 12
	s_cselect_b32 s31, s17, s29
	s_cselect_b32 s30, s23, s28
	s_cselect_b32 s29, s15, s50
	s_cselect_b32 s28, s25, s49
	s_add_i32 s54, 0, 0x14000
	v_add_u32_e32 v134, s52, v245
	v_add_u32_e32 v150, s54, v245
	ds_read_b128 v[122:125], v134
	ds_read_b128 v[126:129], v134 offset:1024
	ds_read_b128 v[130:133], v134 offset:2048
	ds_read_b128 v[134:137], v134 offset:3072
	ds_read_b128 v[138:141], v150
	ds_read_b128 v[142:145], v150 offset:1024
	ds_read_b128 v[146:149], v150 offset:2048
	ds_read_b128 v[150:153], v150 offset:3072
	v_lshl_add_u64 v[200:201], s[26:27], 0, v[204:205]
	s_add_i32 m0, s40, 0xc000
	ds_read_b128 v[162:165], v199
	ds_read_b128 v[166:169], v199 offset:1024
	ds_read_b128 v[170:173], v199 offset:2048
	ds_read_b128 v[174:177], v199 offset:3072
	ds_read_b128 v[178:181], v199 offset:4096
	ds_read_b128 v[182:185], v199 offset:5120
	ds_read_b128 v[186:189], v199 offset:6144
	ds_read_b128 v[194:197], v199 offset:7168
	global_load_lds_dwordx4 v[200:201], off
	v_lshl_add_u64 v[200:201], s[26:27], 0, v[206:207]
	s_add_i32 m0, s40, 0xe000
	s_nop 0
	global_load_lds_dwordx4 v[200:201], off
	s_waitcnt vmcnt(8)
	s_waitcnt lgkmcnt(0)
	s_barrier
	s_setprio 1
	s_waitcnt lgkmcnt(0)
	v_mfma_f32_16x16x32_bf16 v[158:161], v[122:125], v[162:165], 0
	v_mfma_f32_16x16x32_bf16 v[154:157], v[130:133], v[162:165], 0
	v_mfma_f32_16x16x32_bf16 v[110:113], v[122:125], v[170:173], 0
	v_mfma_f32_16x16x32_bf16 v[106:109], v[130:133], v[170:173], 0
	v_mfma_f32_16x16x32_bf16 v[92:95], v[122:125], v[178:181], 0
	v_mfma_f32_16x16x32_bf16 v[88:91], v[130:133], v[178:181], 0
	v_mfma_f32_16x16x32_bf16 v[76:79], v[122:125], v[186:189], 0
	v_mfma_f32_16x16x32_bf16 v[72:75], v[130:133], v[186:189], 0
	v_mfma_f32_16x16x32_bf16 v[158:161], v[126:129], v[166:169], v[158:161]
	v_mfma_f32_16x16x32_bf16 v[154:157], v[134:137], v[166:169], v[154:157]
	v_mfma_f32_16x16x32_bf16 v[110:113], v[126:129], v[174:177], v[110:113]
	v_mfma_f32_16x16x32_bf16 v[106:109], v[134:137], v[174:177], v[106:109]
	v_mfma_f32_16x16x32_bf16 v[92:95], v[126:129], v[182:185], v[92:95]
	v_mfma_f32_16x16x32_bf16 v[88:91], v[134:137], v[182:185], v[88:91]
	v_mfma_f32_16x16x32_bf16 v[76:79], v[126:129], v[194:197], v[76:79]
	v_mfma_f32_16x16x32_bf16 v[72:75], v[134:137], v[194:197], v[72:75]
	s_setprio 0
	s_setprio 1
	v_mfma_f32_16x16x32_bf16 v[118:121], v[138:141], v[162:165], 0
	v_mfma_f32_16x16x32_bf16 v[114:117], v[146:149], v[162:165], 0
	v_mfma_f32_16x16x32_bf16 v[102:105], v[138:141], v[170:173], 0
	v_mfma_f32_16x16x32_bf16 v[98:101], v[146:149], v[170:173], 0
	v_mfma_f32_16x16x32_bf16 v[84:87], v[138:141], v[178:181], 0
	v_mfma_f32_16x16x32_bf16 v[80:83], v[146:149], v[178:181], 0
	v_mfma_f32_16x16x32_bf16 v[68:71], v[138:141], v[186:189], 0
	v_mfma_f32_16x16x32_bf16 v[64:67], v[146:149], v[186:189], 0
	v_mfma_f32_16x16x32_bf16 v[118:121], v[142:145], v[166:169], v[118:121]
	v_mfma_f32_16x16x32_bf16 v[114:117], v[150:153], v[166:169], v[114:117]
	v_mfma_f32_16x16x32_bf16 v[102:105], v[142:145], v[174:177], v[102:105]
	v_mfma_f32_16x16x32_bf16 v[98:101], v[150:153], v[174:177], v[98:101]
	v_mfma_f32_16x16x32_bf16 v[84:87], v[142:145], v[182:185], v[84:87]
	v_mfma_f32_16x16x32_bf16 v[80:83], v[150:153], v[182:185], v[80:83]
	v_mfma_f32_16x16x32_bf16 v[68:71], v[142:145], v[194:197], v[68:71]
	v_mfma_f32_16x16x32_bf16 v[64:67], v[150:153], v[194:197], v[64:67]
	s_setprio 0
	s_barrier
	s_add_i32 s52, s52, s39
	v_lshl_add_u64 v[200:201], s[28:29], 0, v[96:97]
	s_mov_b32 m0, s52
	ds_read_b128 v[162:165], v199 offset:16384
	ds_read_b128 v[166:169], v199 offset:17408
	ds_read_b128 v[170:173], v199 offset:18432
	ds_read_b128 v[174:177], v199 offset:19456
	ds_read_b128 v[178:181], v199 offset:20480
	ds_read_b128 v[182:185], v199 offset:21504
	ds_read_b128 v[186:189], v199 offset:22528
	ds_read_b128 v[194:197], v199 offset:23552
	global_load_lds_dwordx4 v[200:201], off
	s_add_i32 m0, s52, 0x2000
	s_add_u32 s52, s28, 0x40000
	v_lshl_add_u64 v[208:209], s[28:29], 0, v[202:203]
	s_addc_u32 s53, s29, 0
	s_add_i32 s54, s54, s39
	global_load_lds_dwordx4 v[208:209], off
	v_lshl_add_u64 v[210:211], s[52:53], 0, v[96:97]
	s_mov_b32 m0, s54
	v_lshl_add_u64 v[212:213], s[30:31], 0, v[192:193]
	global_load_lds_dwordx4 v[210:211], off
	v_lshl_add_u64 v[210:211], s[52:53], 0, v[202:203]
	s_add_i32 m0, s54, 0x2000
	s_nop 0
	global_load_lds_dwordx4 v[210:211], off
	v_lshl_add_u64 v[210:211], s[30:31], 0, v[190:191]
	s_mov_b32 m0, s40
	s_nop 0
	global_load_lds_dwordx4 v[210:211], off
	s_mov_b32 m0, s41
	s_nop 0
	global_load_lds_dwordx4 v[212:213], off
	s_waitcnt vmcnt(8)
	s_waitcnt lgkmcnt(0)
	s_barrier
	s_setprio 1
	s_waitcnt lgkmcnt(0)
	v_mfma_f32_16x16x32_bf16 v[60:63], v[122:125], v[162:165], 0
	v_mfma_f32_16x16x32_bf16 v[56:59], v[130:133], v[162:165], 0
	v_mfma_f32_16x16x32_bf16 v[44:47], v[122:125], v[170:173], 0
	v_mfma_f32_16x16x32_bf16 v[40:43], v[130:133], v[170:173], 0
	v_mfma_f32_16x16x32_bf16 v[28:31], v[122:125], v[178:181], 0
	v_mfma_f32_16x16x32_bf16 v[24:27], v[130:133], v[178:181], 0
	v_mfma_f32_16x16x32_bf16 v[12:15], v[122:125], v[186:189], 0
	v_mfma_f32_16x16x32_bf16 v[8:11], v[130:133], v[186:189], 0
	v_mfma_f32_16x16x32_bf16 v[60:63], v[126:129], v[166:169], v[60:63]
	v_mfma_f32_16x16x32_bf16 v[56:59], v[134:137], v[166:169], v[56:59]
	v_mfma_f32_16x16x32_bf16 v[44:47], v[126:129], v[174:177], v[44:47]
	v_mfma_f32_16x16x32_bf16 v[40:43], v[134:137], v[174:177], v[40:43]
	v_mfma_f32_16x16x32_bf16 v[28:31], v[126:129], v[182:185], v[28:31]
	v_mfma_f32_16x16x32_bf16 v[24:27], v[134:137], v[182:185], v[24:27]
	v_mfma_f32_16x16x32_bf16 v[12:15], v[126:129], v[194:197], v[12:15]
	v_mfma_f32_16x16x32_bf16 v[8:11], v[134:137], v[194:197], v[8:11]
	s_setprio 0
	s_setprio 1
	v_mfma_f32_16x16x32_bf16 v[52:55], v[138:141], v[162:165], 0
	v_mfma_f32_16x16x32_bf16 v[48:51], v[146:149], v[162:165], 0
	v_mfma_f32_16x16x32_bf16 v[36:39], v[138:141], v[170:173], 0
	v_mfma_f32_16x16x32_bf16 v[32:35], v[146:149], v[170:173], 0
	v_mfma_f32_16x16x32_bf16 v[20:23], v[138:141], v[178:181], 0
	v_mfma_f32_16x16x32_bf16 v[16:19], v[146:149], v[178:181], 0
	v_mfma_f32_16x16x32_bf16 v[4:7], v[138:141], v[186:189], 0
	v_mfma_f32_16x16x32_bf16 v[0:3], v[146:149], v[186:189], 0
	v_mfma_f32_16x16x32_bf16 v[52:55], v[142:145], v[166:169], v[52:55]
	v_mfma_f32_16x16x32_bf16 v[48:51], v[150:153], v[166:169], v[48:51]
	v_mfma_f32_16x16x32_bf16 v[36:39], v[142:145], v[174:177], v[36:39]
	v_mfma_f32_16x16x32_bf16 v[32:35], v[150:153], v[174:177], v[32:35]
	v_mfma_f32_16x16x32_bf16 v[20:23], v[142:145], v[182:185], v[20:23]
	v_mfma_f32_16x16x32_bf16 v[16:19], v[150:153], v[182:185], v[16:19]
	v_mfma_f32_16x16x32_bf16 v[4:7], v[142:145], v[194:197], v[4:7]
	v_mfma_f32_16x16x32_bf16 v[0:3], v[150:153], v[194:197], v[0:3]
	s_setprio 0
	s_barrier
	s_add_i32 s52, 0, 0x18000
	s_add_i32 s53, 0, 0x1c000
	v_add_u32_e32 v134, s52, v245
	v_add_u32_e32 v150, s53, v245
	ds_read_b128 v[122:125], v134
	ds_read_b128 v[126:129], v134 offset:1024
	ds_read_b128 v[130:133], v134 offset:2048
	ds_read_b128 v[134:137], v134 offset:3072
	ds_read_b128 v[138:141], v150
	ds_read_b128 v[142:145], v150 offset:1024
	ds_read_b128 v[146:149], v150 offset:2048
	ds_read_b128 v[150:153], v150 offset:3072
	s_add_u32 s30, s30, 0x40000
	s_addc_u32 s31, s31, 0
	s_mov_b32 m0, s42
	v_lshl_add_u64 v[214:215], s[30:31], 0, v[190:191]
	ds_read_b128 v[162:165], v199 offset:32768
	ds_read_b128 v[166:169], v199 offset:33792
	ds_read_b128 v[170:173], v199 offset:34816
	ds_read_b128 v[174:177], v199 offset:35840
	ds_read_b128 v[178:181], v199 offset:36864
	ds_read_b128 v[182:185], v199 offset:37888
	ds_read_b128 v[186:189], v199 offset:38912
	ds_read_b128 v[194:197], v199 offset:39936
	global_load_lds_dwordx4 v[214:215], off
	v_lshl_add_u64 v[214:215], s[30:31], 0, v[192:193]
	s_mov_b32 m0, s43
	s_nop 0
	global_load_lds_dwordx4 v[214:215], off
	s_waitcnt vmcnt(8)
	s_waitcnt lgkmcnt(0)
	s_barrier
	s_setprio 1
	s_waitcnt lgkmcnt(0)
	v_mfma_f32_16x16x32_bf16 v[158:161], v[122:125], v[162:165], v[158:161]
	v_mfma_f32_16x16x32_bf16 v[154:157], v[130:133], v[162:165], v[154:157]
	v_mfma_f32_16x16x32_bf16 v[110:113], v[122:125], v[170:173], v[110:113]
	v_mfma_f32_16x16x32_bf16 v[106:109], v[130:133], v[170:173], v[106:109]
	v_mfma_f32_16x16x32_bf16 v[92:95], v[122:125], v[178:181], v[92:95]
	v_mfma_f32_16x16x32_bf16 v[88:91], v[130:133], v[178:181], v[88:91]
	v_mfma_f32_16x16x32_bf16 v[76:79], v[122:125], v[186:189], v[76:79]
	v_mfma_f32_16x16x32_bf16 v[72:75], v[130:133], v[186:189], v[72:75]
	v_mfma_f32_16x16x32_bf16 v[158:161], v[126:129], v[166:169], v[158:161]
	v_mfma_f32_16x16x32_bf16 v[154:157], v[134:137], v[166:169], v[154:157]
	v_mfma_f32_16x16x32_bf16 v[110:113], v[126:129], v[174:177], v[110:113]
	v_mfma_f32_16x16x32_bf16 v[106:109], v[134:137], v[174:177], v[106:109]
	v_mfma_f32_16x16x32_bf16 v[92:95], v[126:129], v[182:185], v[92:95]
	v_mfma_f32_16x16x32_bf16 v[88:91], v[134:137], v[182:185], v[88:91]
	v_mfma_f32_16x16x32_bf16 v[76:79], v[126:129], v[194:197], v[76:79]
	v_mfma_f32_16x16x32_bf16 v[72:75], v[134:137], v[194:197], v[72:75]
	s_setprio 0
	s_setprio 1
	v_mfma_f32_16x16x32_bf16 v[118:121], v[138:141], v[162:165], v[118:121]
	v_mfma_f32_16x16x32_bf16 v[114:117], v[146:149], v[162:165], v[114:117]
	v_mfma_f32_16x16x32_bf16 v[102:105], v[138:141], v[170:173], v[102:105]
	v_mfma_f32_16x16x32_bf16 v[98:101], v[146:149], v[170:173], v[98:101]
	v_mfma_f32_16x16x32_bf16 v[84:87], v[138:141], v[178:181], v[84:87]
	v_mfma_f32_16x16x32_bf16 v[80:83], v[146:149], v[178:181], v[80:83]
	v_mfma_f32_16x16x32_bf16 v[68:71], v[138:141], v[186:189], v[68:71]
	v_mfma_f32_16x16x32_bf16 v[64:67], v[146:149], v[186:189], v[64:67]
	v_mfma_f32_16x16x32_bf16 v[118:121], v[142:145], v[166:169], v[118:121]
	v_mfma_f32_16x16x32_bf16 v[114:117], v[150:153], v[166:169], v[114:117]
	v_mfma_f32_16x16x32_bf16 v[102:105], v[142:145], v[174:177], v[102:105]
	v_mfma_f32_16x16x32_bf16 v[98:101], v[150:153], v[174:177], v[98:101]
	v_mfma_f32_16x16x32_bf16 v[84:87], v[142:145], v[182:185], v[84:87]
	v_mfma_f32_16x16x32_bf16 v[80:83], v[150:153], v[182:185], v[80:83]
	v_mfma_f32_16x16x32_bf16 v[68:71], v[142:145], v[194:197], v[68:71]
	v_mfma_f32_16x16x32_bf16 v[64:67], v[150:153], v[194:197], v[64:67]
	s_setprio 0
	s_barrier
	s_add_i32 s30, s52, s39
	v_lshl_add_u64 v[200:201], v[200:201], 0, s[64:65]
	s_mov_b32 m0, s30
	ds_read_b128 v[162:165], v199 offset:49152
	ds_read_b128 v[166:169], v199 offset:50176
	ds_read_b128 v[170:173], v199 offset:51200
	ds_read_b128 v[174:177], v199 offset:52224
	ds_read_b128 v[178:181], v199 offset:53248
	ds_read_b128 v[182:185], v199 offset:54272
	ds_read_b128 v[186:189], v199 offset:55296
	ds_read_b128 v[194:197], v199 offset:56320
	global_load_lds_dwordx4 v[200:201], off
	s_add_i32 m0, s30, 0x2000
	s_add_u32 s28, s28, 0x40080
	v_lshl_add_u64 v[200:201], v[208:209], 0, s[64:65]
	s_addc_u32 s29, s29, 0
	s_add_i32 s30, s53, s39
	global_load_lds_dwordx4 v[200:201], off
	v_lshl_add_u64 v[200:201], s[28:29], 0, v[96:97]
	s_mov_b32 m0, s30
	s_nop 0
	global_load_lds_dwordx4 v[200:201], off
	v_lshl_add_u64 v[200:201], s[28:29], 0, v[202:203]
	s_add_i32 m0, s30, 0x2000
	s_nop 0
	global_load_lds_dwordx4 v[200:201], off
	v_lshl_add_u64 v[200:201], v[210:211], 0, s[64:65]
	s_mov_b32 m0, s45
	s_nop 0
	global_load_lds_dwordx4 v[200:201], off
	v_lshl_add_u64 v[200:201], v[212:213], 0, s[64:65]
	s_mov_b32 m0, s46
	s_nop 0
	global_load_lds_dwordx4 v[200:201], off
	s_waitcnt vmcnt(8)
	s_waitcnt lgkmcnt(0)
	s_barrier
	s_setprio 1
	s_waitcnt lgkmcnt(0)
	v_mfma_f32_16x16x32_bf16 v[60:63], v[122:125], v[162:165], v[60:63]
	v_mfma_f32_16x16x32_bf16 v[56:59], v[130:133], v[162:165], v[56:59]
	v_mfma_f32_16x16x32_bf16 v[44:47], v[122:125], v[170:173], v[44:47]
	v_mfma_f32_16x16x32_bf16 v[40:43], v[130:133], v[170:173], v[40:43]
	v_mfma_f32_16x16x32_bf16 v[28:31], v[122:125], v[178:181], v[28:31]
	v_mfma_f32_16x16x32_bf16 v[24:27], v[130:133], v[178:181], v[24:27]
	v_mfma_f32_16x16x32_bf16 v[12:15], v[122:125], v[186:189], v[12:15]
	v_mfma_f32_16x16x32_bf16 v[8:11], v[130:133], v[186:189], v[8:11]
	v_mfma_f32_16x16x32_bf16 v[60:63], v[126:129], v[166:169], v[60:63]
	v_mfma_f32_16x16x32_bf16 v[56:59], v[134:137], v[166:169], v[56:59]
	v_mfma_f32_16x16x32_bf16 v[44:47], v[126:129], v[174:177], v[44:47]
	v_mfma_f32_16x16x32_bf16 v[40:43], v[134:137], v[174:177], v[40:43]
	v_mfma_f32_16x16x32_bf16 v[28:31], v[126:129], v[182:185], v[28:31]
	v_mfma_f32_16x16x32_bf16 v[24:27], v[134:137], v[182:185], v[24:27]
	v_mfma_f32_16x16x32_bf16 v[12:15], v[126:129], v[194:197], v[12:15]
	v_mfma_f32_16x16x32_bf16 v[8:11], v[134:137], v[194:197], v[8:11]
	s_setprio 0
	s_setprio 1
	v_mfma_f32_16x16x32_bf16 v[52:55], v[138:141], v[162:165], v[52:55]
	v_mfma_f32_16x16x32_bf16 v[48:51], v[146:149], v[162:165], v[48:51]
	v_mfma_f32_16x16x32_bf16 v[36:39], v[138:141], v[170:173], v[36:39]
	v_mfma_f32_16x16x32_bf16 v[32:35], v[146:149], v[170:173], v[32:35]
	v_mfma_f32_16x16x32_bf16 v[20:23], v[138:141], v[178:181], v[20:23]
	v_mfma_f32_16x16x32_bf16 v[16:19], v[146:149], v[178:181], v[16:19]
	v_mfma_f32_16x16x32_bf16 v[4:7], v[138:141], v[186:189], v[4:7]
	v_mfma_f32_16x16x32_bf16 v[0:3], v[146:149], v[186:189], v[0:3]
	v_mfma_f32_16x16x32_bf16 v[52:55], v[142:145], v[166:169], v[52:55]
	v_mfma_f32_16x16x32_bf16 v[48:51], v[150:153], v[166:169], v[48:51]
	v_mfma_f32_16x16x32_bf16 v[36:39], v[142:145], v[174:177], v[36:39]
	v_mfma_f32_16x16x32_bf16 v[32:35], v[150:153], v[174:177], v[32:35]
	v_mfma_f32_16x16x32_bf16 v[20:23], v[142:145], v[182:185], v[20:23]
	v_mfma_f32_16x16x32_bf16 v[16:19], v[150:153], v[182:185], v[16:19]
	v_mfma_f32_16x16x32_bf16 v[4:7], v[142:145], v[194:197], v[4:7]
	v_mfma_f32_16x16x32_bf16 v[0:3], v[150:153], v[194:197], v[0:3]
	s_setprio 0
	s_barrier
	s_add_i32 s51, s51, 2
	s_add_u32 s26, s26, 0x100
	s_addc_u32 s27, s27, 0
	s_add_u32 s49, s49, 0x100
	s_addc_u32 s50, s50, 0
	s_cmp_gt_u32 s51, 13
	s_cbranch_scc1 .Lpeel_done_634
	.p2align 6

.LBB0_721:
	s_ashr_i32 s17, s16, 31
	s_lshl_b64 s[18:19], s[16:17], 19
	s_add_u32 s18, s35, s18
	s_addc_u32 s19, s36, s19
	s_and_b64 s[20:21], s[2:3], exec
	s_cselect_b32 s17, s19, s25
	s_cselect_b32 s48, s18, s24
	s_ashr_i32 s15, s14, 31
	s_lshl_b64 s[20:21], s[14:15], 19
	s_add_u32 s20, s31, s20
	s_addc_u32 s21, s34, s21
	s_and_b64 s[28:29], s[2:3], exec
	s_cselect_b32 s15, s21, s27
	s_cselect_b32 s49, s20, s26
	s_add_u32 s24, s24, 0x40080
	s_addc_u32 s25, s25, 0
	s_add_u32 s50, s26, 0x100
	s_addc_u32 s51, s27, 0
	s_mov_b32 s52, -2
	s_add_u32 s26, s24, 0xfffc0080
	s_addc_u32 s27, s25, -1
	s_add_i32 s53, 0, 0x10000
	s_cmp_eq_u32 s52, 12
	s_cselect_b32 s29, s17, s27
	s_cselect_b32 s28, s48, s26
	v_add_u32_e32 v147, s53, v141
	s_cselect_b32 s27, s15, s51
	s_cselect_b32 s26, s49, s50
	s_add_i32 s56, 0, 0x14000
	ds_read_b128 v[148:151], v147
	ds_read_b128 v[152:155], v147 offset:1024
	ds_read_b128 v[156:159], v147 offset:2048
	ds_read_b128 v[160:163], v147 offset:3072
	v_add_u32_e32 v147, s56, v141
	ds_read_b128 v[164:167], v147
	ds_read_b128 v[168:171], v147 offset:1024
	ds_read_b128 v[172:175], v147 offset:2048
	ds_read_b128 v[176:179], v147 offset:3072
	v_lshl_add_u64 v[192:193], s[24:25], 0, v[136:137]
	s_add_i32 m0, s23, 0xc000
	ds_read_b128 v[180:183], v146
	ds_read_b128 v[184:187], v146 offset:1024
	ds_read_b128 v[188:191], v146 offset:2048
	ds_read_b128 v[202:205], v146 offset:3072
	ds_read_b128 v[206:209], v146 offset:4096
	ds_read_b128 v[210:213], v146 offset:5120
	ds_read_b128 v[214:217], v146 offset:6144
	ds_read_b128 v[218:221], v146 offset:7168
	global_load_lds_dwordx4 v[192:193], off
	v_lshl_add_u64 v[192:193], s[24:25], 0, v[138:139]
	s_add_i32 m0, s23, 0xe000
	s_nop 0
	global_load_lds_dwordx4 v[192:193], off
	s_waitcnt vmcnt(8)
	s_waitcnt lgkmcnt(0)
	s_barrier
	s_setprio 1
	s_waitcnt lgkmcnt(0)
	v_mfma_f32_16x16x32_bf16 v[126:129], v[148:151], v[180:183], 0
	v_mfma_f32_16x16x32_bf16 v[122:125], v[156:159], v[180:183], 0
	v_mfma_f32_16x16x32_bf16 v[114:117], v[148:151], v[188:191], 0
	v_mfma_f32_16x16x32_bf16 v[106:109], v[156:159], v[188:191], 0
	v_mfma_f32_16x16x32_bf16 v[98:101], v[148:151], v[206:209], 0
	v_mfma_f32_16x16x32_bf16 v[88:91], v[156:159], v[206:209], 0
	v_mfma_f32_16x16x32_bf16 v[80:83], v[148:151], v[214:217], 0
	v_mfma_f32_16x16x32_bf16 v[72:75], v[156:159], v[214:217], 0
	v_mfma_f32_16x16x32_bf16 v[126:129], v[152:155], v[184:187], v[126:129]
	v_mfma_f32_16x16x32_bf16 v[122:125], v[160:163], v[184:187], v[122:125]
	v_mfma_f32_16x16x32_bf16 v[114:117], v[152:155], v[202:205], v[114:117]
	v_mfma_f32_16x16x32_bf16 v[106:109], v[160:163], v[202:205], v[106:109]
	v_mfma_f32_16x16x32_bf16 v[98:101], v[152:155], v[210:213], v[98:101]
	v_mfma_f32_16x16x32_bf16 v[88:91], v[160:163], v[210:213], v[88:91]
	v_mfma_f32_16x16x32_bf16 v[80:83], v[152:155], v[218:221], v[80:83]
	v_mfma_f32_16x16x32_bf16 v[72:75], v[160:163], v[218:221], v[72:75]
	s_setprio 0
	s_setprio 1
	v_mfma_f32_16x16x32_bf16 v[118:121], v[164:167], v[180:183], 0
	v_mfma_f32_16x16x32_bf16 v[110:113], v[172:175], v[180:183], 0
	v_mfma_f32_16x16x32_bf16 v[102:105], v[164:167], v[188:191], 0
	v_mfma_f32_16x16x32_bf16 v[92:95], v[172:175], v[188:191], 0
	v_mfma_f32_16x16x32_bf16 v[84:87], v[164:167], v[206:209], 0
	v_mfma_f32_16x16x32_bf16 v[76:79], v[172:175], v[206:209], 0
	v_mfma_f32_16x16x32_bf16 v[68:71], v[164:167], v[214:217], 0
	v_mfma_f32_16x16x32_bf16 v[64:67], v[172:175], v[214:217], 0
	v_mfma_f32_16x16x32_bf16 v[118:121], v[168:171], v[184:187], v[118:121]
	v_mfma_f32_16x16x32_bf16 v[110:113], v[176:179], v[184:187], v[110:113]
	v_mfma_f32_16x16x32_bf16 v[102:105], v[168:171], v[202:205], v[102:105]
	v_mfma_f32_16x16x32_bf16 v[92:95], v[176:179], v[202:205], v[92:95]
	v_mfma_f32_16x16x32_bf16 v[84:87], v[168:171], v[210:213], v[84:87]
	v_mfma_f32_16x16x32_bf16 v[76:79], v[176:179], v[210:213], v[76:79]
	v_mfma_f32_16x16x32_bf16 v[68:71], v[168:171], v[218:221], v[68:71]
	v_mfma_f32_16x16x32_bf16 v[64:67], v[176:179], v[218:221], v[64:67]
	s_setprio 0
	s_barrier
	s_add_i32 s53, s53, s38
	v_lshl_add_u64 v[192:193], s[26:27], 0, v[96:97]
	s_mov_b32 m0, s53
	ds_read_b128 v[180:183], v146 offset:16384
	ds_read_b128 v[184:187], v146 offset:17408
	ds_read_b128 v[188:191], v146 offset:18432
	ds_read_b128 v[202:205], v146 offset:19456
	ds_read_b128 v[206:209], v146 offset:20480
	ds_read_b128 v[210:213], v146 offset:21504
	ds_read_b128 v[214:217], v146 offset:22528
	ds_read_b128 v[218:221], v146 offset:23552
	global_load_lds_dwordx4 v[192:193], off
	s_add_i32 m0, s53, 0x2000
	s_add_u32 s54, s26, 0x40000
	v_lshl_add_u64 v[194:195], s[26:27], 0, v[130:131]
	s_addc_u32 s55, s27, 0
	s_add_i32 s53, s56, s38
	global_load_lds_dwordx4 v[194:195], off
	v_lshl_add_u64 v[196:197], s[54:55], 0, v[96:97]
	s_mov_b32 m0, s53
	v_lshl_add_u64 v[198:199], s[28:29], 0, v[132:133]
	global_load_lds_dwordx4 v[196:197], off
	v_lshl_add_u64 v[196:197], s[54:55], 0, v[130:131]
	s_add_i32 m0, s53, 0x2000
	s_nop 0
	global_load_lds_dwordx4 v[196:197], off
	v_lshl_add_u64 v[196:197], s[28:29], 0, v[134:135]
	s_mov_b32 m0, s23
	s_nop 0
	global_load_lds_dwordx4 v[196:197], off
	s_mov_b32 m0, s39
	s_nop 0
	global_load_lds_dwordx4 v[198:199], off
	s_waitcnt vmcnt(8)
	s_waitcnt lgkmcnt(0)
	s_barrier
	s_setprio 1
	s_waitcnt lgkmcnt(0)
	v_mfma_f32_16x16x32_bf16 v[60:63], v[148:151], v[180:183], 0
	v_mfma_f32_16x16x32_bf16 v[56:59], v[156:159], v[180:183], 0
	v_mfma_f32_16x16x32_bf16 v[48:51], v[148:151], v[188:191], 0
	v_mfma_f32_16x16x32_bf16 v[40:43], v[156:159], v[188:191], 0
	v_mfma_f32_16x16x32_bf16 v[32:35], v[148:151], v[206:209], 0
	v_mfma_f32_16x16x32_bf16 v[24:27], v[156:159], v[206:209], 0
	v_mfma_f32_16x16x32_bf16 v[16:19], v[148:151], v[214:217], 0
	v_mfma_f32_16x16x32_bf16 v[8:11], v[156:159], v[214:217], 0
	v_mfma_f32_16x16x32_bf16 v[60:63], v[152:155], v[184:187], v[60:63]
	v_mfma_f32_16x16x32_bf16 v[56:59], v[160:163], v[184:187], v[56:59]
	v_mfma_f32_16x16x32_bf16 v[48:51], v[152:155], v[202:205], v[48:51]
	v_mfma_f32_16x16x32_bf16 v[40:43], v[160:163], v[202:205], v[40:43]
	v_mfma_f32_16x16x32_bf16 v[32:35], v[152:155], v[210:213], v[32:35]
	v_mfma_f32_16x16x32_bf16 v[24:27], v[160:163], v[210:213], v[24:27]
	v_mfma_f32_16x16x32_bf16 v[16:19], v[152:155], v[218:221], v[16:19]
	v_mfma_f32_16x16x32_bf16 v[8:11], v[160:163], v[218:221], v[8:11]
	s_setprio 0
	s_setprio 1
	v_mfma_f32_16x16x32_bf16 v[52:55], v[164:167], v[180:183], 0
	v_mfma_f32_16x16x32_bf16 v[44:47], v[172:175], v[180:183], 0
	v_mfma_f32_16x16x32_bf16 v[36:39], v[164:167], v[188:191], 0
	v_mfma_f32_16x16x32_bf16 v[28:31], v[172:175], v[188:191], 0
	v_mfma_f32_16x16x32_bf16 v[20:23], v[164:167], v[206:209], 0
	v_mfma_f32_16x16x32_bf16 v[12:15], v[172:175], v[206:209], 0
	v_mfma_f32_16x16x32_bf16 v[4:7], v[164:167], v[214:217], 0
	v_mfma_f32_16x16x32_bf16 v[0:3], v[172:175], v[214:217], 0
	v_mfma_f32_16x16x32_bf16 v[52:55], v[168:171], v[184:187], v[52:55]
	v_mfma_f32_16x16x32_bf16 v[44:47], v[176:179], v[184:187], v[44:47]
	v_mfma_f32_16x16x32_bf16 v[36:39], v[168:171], v[202:205], v[36:39]
	v_mfma_f32_16x16x32_bf16 v[28:31], v[176:179], v[202:205], v[28:31]
	v_mfma_f32_16x16x32_bf16 v[20:23], v[168:171], v[210:213], v[20:23]
	v_mfma_f32_16x16x32_bf16 v[12:15], v[176:179], v[210:213], v[12:15]
	v_mfma_f32_16x16x32_bf16 v[4:7], v[168:171], v[218:221], v[4:7]
	v_mfma_f32_16x16x32_bf16 v[0:3], v[176:179], v[218:221], v[0:3]
	s_setprio 0
	s_barrier
	s_add_i32 s53, 0, 0x18000
	v_add_u32_e32 v147, s53, v141
	s_add_i32 s54, 0, 0x1c000
	ds_read_b128 v[148:151], v147
	ds_read_b128 v[152:155], v147 offset:1024
	ds_read_b128 v[156:159], v147 offset:2048
	ds_read_b128 v[160:163], v147 offset:3072
	v_add_u32_e32 v147, s54, v141
	ds_read_b128 v[164:167], v147
	ds_read_b128 v[168:171], v147 offset:1024
	ds_read_b128 v[172:175], v147 offset:2048
	ds_read_b128 v[176:179], v147 offset:3072
	s_add_u32 s28, s28, 0x40000
	s_addc_u32 s29, s29, 0
	s_mov_b32 m0, s40
	v_lshl_add_u64 v[200:201], s[28:29], 0, v[134:135]
	ds_read_b128 v[180:183], v146 offset:32768
	ds_read_b128 v[184:187], v146 offset:33792
	ds_read_b128 v[188:191], v146 offset:34816
	ds_read_b128 v[202:205], v146 offset:35840
	ds_read_b128 v[206:209], v146 offset:36864
	ds_read_b128 v[210:213], v146 offset:37888
	ds_read_b128 v[214:217], v146 offset:38912
	ds_read_b128 v[218:221], v146 offset:39936
	global_load_lds_dwordx4 v[200:201], off
	v_lshl_add_u64 v[200:201], s[28:29], 0, v[132:133]
	s_mov_b32 m0, s41
	s_nop 0
	global_load_lds_dwordx4 v[200:201], off
	s_waitcnt vmcnt(8)
	s_waitcnt lgkmcnt(0)
	s_barrier
	s_setprio 1
	s_waitcnt lgkmcnt(0)
	v_mfma_f32_16x16x32_bf16 v[126:129], v[148:151], v[180:183], v[126:129]
	v_mfma_f32_16x16x32_bf16 v[122:125], v[156:159], v[180:183], v[122:125]
	v_mfma_f32_16x16x32_bf16 v[114:117], v[148:151], v[188:191], v[114:117]
	v_mfma_f32_16x16x32_bf16 v[106:109], v[156:159], v[188:191], v[106:109]
	v_mfma_f32_16x16x32_bf16 v[98:101], v[148:151], v[206:209], v[98:101]
	v_mfma_f32_16x16x32_bf16 v[88:91], v[156:159], v[206:209], v[88:91]
	v_mfma_f32_16x16x32_bf16 v[80:83], v[148:151], v[214:217], v[80:83]
	v_mfma_f32_16x16x32_bf16 v[72:75], v[156:159], v[214:217], v[72:75]
	v_mfma_f32_16x16x32_bf16 v[126:129], v[152:155], v[184:187], v[126:129]
	v_mfma_f32_16x16x32_bf16 v[122:125], v[160:163], v[184:187], v[122:125]
	v_mfma_f32_16x16x32_bf16 v[114:117], v[152:155], v[202:205], v[114:117]
	v_mfma_f32_16x16x32_bf16 v[106:109], v[160:163], v[202:205], v[106:109]
	v_mfma_f32_16x16x32_bf16 v[98:101], v[152:155], v[210:213], v[98:101]
	v_mfma_f32_16x16x32_bf16 v[88:91], v[160:163], v[210:213], v[88:91]
	v_mfma_f32_16x16x32_bf16 v[80:83], v[152:155], v[218:221], v[80:83]
	v_mfma_f32_16x16x32_bf16 v[72:75], v[160:163], v[218:221], v[72:75]
	s_setprio 0
	s_setprio 1
	v_mfma_f32_16x16x32_bf16 v[118:121], v[164:167], v[180:183], v[118:121]
	v_mfma_f32_16x16x32_bf16 v[110:113], v[172:175], v[180:183], v[110:113]
	v_mfma_f32_16x16x32_bf16 v[102:105], v[164:167], v[188:191], v[102:105]
	v_mfma_f32_16x16x32_bf16 v[92:95], v[172:175], v[188:191], v[92:95]
	v_mfma_f32_16x16x32_bf16 v[84:87], v[164:167], v[206:209], v[84:87]
	v_mfma_f32_16x16x32_bf16 v[76:79], v[172:175], v[206:209], v[76:79]
	v_mfma_f32_16x16x32_bf16 v[68:71], v[164:167], v[214:217], v[68:71]
	v_mfma_f32_16x16x32_bf16 v[64:67], v[172:175], v[214:217], v[64:67]
	v_mfma_f32_16x16x32_bf16 v[118:121], v[168:171], v[184:187], v[118:121]
	v_mfma_f32_16x16x32_bf16 v[110:113], v[176:179], v[184:187], v[110:113]
	v_mfma_f32_16x16x32_bf16 v[102:105], v[168:171], v[202:205], v[102:105]
	v_mfma_f32_16x16x32_bf16 v[92:95], v[176:179], v[202:205], v[92:95]
	v_mfma_f32_16x16x32_bf16 v[84:87], v[168:171], v[210:213], v[84:87]
	v_mfma_f32_16x16x32_bf16 v[76:79], v[176:179], v[210:213], v[76:79]
	v_mfma_f32_16x16x32_bf16 v[68:71], v[168:171], v[218:221], v[68:71]
	v_mfma_f32_16x16x32_bf16 v[64:67], v[176:179], v[218:221], v[64:67]
	s_setprio 0
	s_barrier
	s_add_i32 s28, s53, s38
	v_lshl_add_u64 v[192:193], v[192:193], 0, s[64:65]
	s_mov_b32 m0, s28
	ds_read_b128 v[180:183], v146 offset:49152
	ds_read_b128 v[184:187], v146 offset:50176
	ds_read_b128 v[188:191], v146 offset:51200
	ds_read_b128 v[202:205], v146 offset:52224
	ds_read_b128 v[206:209], v146 offset:53248
	ds_read_b128 v[210:213], v146 offset:54272
	ds_read_b128 v[214:217], v146 offset:55296
	ds_read_b128 v[218:221], v146 offset:56320
	global_load_lds_dwordx4 v[192:193], off
	s_add_i32 m0, s28, 0x2000
	s_add_u32 s26, s26, 0x40080
	v_lshl_add_u64 v[192:193], v[194:195], 0, s[64:65]
	s_addc_u32 s27, s27, 0
	s_add_i32 s28, s54, s38
	global_load_lds_dwordx4 v[192:193], off
	v_lshl_add_u64 v[192:193], s[26:27], 0, v[96:97]
	s_mov_b32 m0, s28
	s_nop 0
	global_load_lds_dwordx4 v[192:193], off
	v_lshl_add_u64 v[192:193], s[26:27], 0, v[130:131]
	s_add_i32 m0, s28, 0x2000
	s_nop 0
	global_load_lds_dwordx4 v[192:193], off
	v_lshl_add_u64 v[192:193], v[196:197], 0, s[64:65]
	s_mov_b32 m0, s42
	s_nop 0
	global_load_lds_dwordx4 v[192:193], off
	v_lshl_add_u64 v[192:193], v[198:199], 0, s[64:65]
	s_mov_b32 m0, s43
	s_nop 0
	global_load_lds_dwordx4 v[192:193], off
	s_waitcnt vmcnt(8)
	s_waitcnt lgkmcnt(0)
	s_barrier
	s_setprio 1
	s_waitcnt lgkmcnt(0)
	v_mfma_f32_16x16x32_bf16 v[60:63], v[148:151], v[180:183], v[60:63]
	v_mfma_f32_16x16x32_bf16 v[56:59], v[156:159], v[180:183], v[56:59]
	v_mfma_f32_16x16x32_bf16 v[48:51], v[148:151], v[188:191], v[48:51]
	v_mfma_f32_16x16x32_bf16 v[40:43], v[156:159], v[188:191], v[40:43]
	v_mfma_f32_16x16x32_bf16 v[32:35], v[148:151], v[206:209], v[32:35]
	v_mfma_f32_16x16x32_bf16 v[24:27], v[156:159], v[206:209], v[24:27]
	v_mfma_f32_16x16x32_bf16 v[16:19], v[148:151], v[214:217], v[16:19]
	v_mfma_f32_16x16x32_bf16 v[8:11], v[156:159], v[214:217], v[8:11]
	v_mfma_f32_16x16x32_bf16 v[60:63], v[152:155], v[184:187], v[60:63]
	v_mfma_f32_16x16x32_bf16 v[56:59], v[160:163], v[184:187], v[56:59]
	v_mfma_f32_16x16x32_bf16 v[48:51], v[152:155], v[202:205], v[48:51]
	v_mfma_f32_16x16x32_bf16 v[40:43], v[160:163], v[202:205], v[40:43]
	v_mfma_f32_16x16x32_bf16 v[32:35], v[152:155], v[210:213], v[32:35]
	v_mfma_f32_16x16x32_bf16 v[24:27], v[160:163], v[210:213], v[24:27]
	v_mfma_f32_16x16x32_bf16 v[16:19], v[152:155], v[218:221], v[16:19]
	v_mfma_f32_16x16x32_bf16 v[8:11], v[160:163], v[218:221], v[8:11]
	s_setprio 0
	s_setprio 1
	v_mfma_f32_16x16x32_bf16 v[52:55], v[164:167], v[180:183], v[52:55]
	v_mfma_f32_16x16x32_bf16 v[44:47], v[172:175], v[180:183], v[44:47]
	v_mfma_f32_16x16x32_bf16 v[36:39], v[164:167], v[188:191], v[36:39]
	v_mfma_f32_16x16x32_bf16 v[28:31], v[172:175], v[188:191], v[28:31]
	v_mfma_f32_16x16x32_bf16 v[20:23], v[164:167], v[206:209], v[20:23]
	v_mfma_f32_16x16x32_bf16 v[12:15], v[172:175], v[206:209], v[12:15]
	v_mfma_f32_16x16x32_bf16 v[4:7], v[164:167], v[214:217], v[4:7]
	v_mfma_f32_16x16x32_bf16 v[0:3], v[172:175], v[214:217], v[0:3]
	v_mfma_f32_16x16x32_bf16 v[52:55], v[168:171], v[184:187], v[52:55]
	v_mfma_f32_16x16x32_bf16 v[44:47], v[176:179], v[184:187], v[44:47]
	v_mfma_f32_16x16x32_bf16 v[36:39], v[168:171], v[202:205], v[36:39]
	v_mfma_f32_16x16x32_bf16 v[28:31], v[176:179], v[202:205], v[28:31]
	v_mfma_f32_16x16x32_bf16 v[20:23], v[168:171], v[210:213], v[20:23]
	v_mfma_f32_16x16x32_bf16 v[12:15], v[176:179], v[210:213], v[12:15]
	v_mfma_f32_16x16x32_bf16 v[4:7], v[168:171], v[218:221], v[4:7]
	v_mfma_f32_16x16x32_bf16 v[0:3], v[176:179], v[218:221], v[0:3]
	s_setprio 0
	s_barrier
	s_add_i32 s52, s52, 2
	s_add_u32 s24, s24, 0x100
	s_addc_u32 s25, s25, 0
	s_add_u32 s50, s50, 0x100
	s_addc_u32 s51, s51, 0
	s_cmp_gt_u32 s52, 13
	s_cbranch_scc1 .Lpeel_done_722
	.p2align 6

.LBB0_860:
	s_add_u32 s48, s20, 0x100
	s_addc_u32 s49, s21, 0
	s_mov_b32 s50, -2
	s_add_u32 s20, s18, 0x100
	s_addc_u32 s21, s19, 0
	s_add_i32 s51, 0, 0x10000
	s_cmp_eq_u32 s50, 2
	s_cselect_b32 s25, s5, s21
	s_cselect_b32 s24, s4, s20
	v_add_u32_e32 v147, s51, v141
	s_cselect_b32 s23, s17, s49
	s_cselect_b32 s22, s16, s48
	s_add_i32 s52, 0, 0x14000
	ds_read_b128 v[148:151], v147
	ds_read_b128 v[152:155], v147 offset:1024
	ds_read_b128 v[156:159], v147 offset:2048
	ds_read_b128 v[160:163], v147 offset:3072
	v_add_u32_e32 v147, s52, v141
	ds_read_b128 v[164:167], v147
	ds_read_b128 v[168:171], v147 offset:1024
	ds_read_b128 v[172:175], v147 offset:2048
	ds_read_b128 v[176:179], v147 offset:3072
	v_lshl_add_u64 v[192:193], s[18:19], 0, v[136:137]
	s_add_i32 m0, s35, 0xc000
	ds_read_b128 v[180:183], v146
	ds_read_b128 v[184:187], v146 offset:1024
	ds_read_b128 v[188:191], v146 offset:2048
	ds_read_b128 v[202:205], v146 offset:3072
	ds_read_b128 v[206:209], v146 offset:4096
	ds_read_b128 v[210:213], v146 offset:5120
	ds_read_b128 v[214:217], v146 offset:6144
	ds_read_b128 v[218:221], v146 offset:7168
	global_load_lds_dwordx4 v[192:193], off
	v_lshl_add_u64 v[192:193], s[18:19], 0, v[138:139]
	s_add_i32 m0, s35, 0xe000
	s_nop 0
	global_load_lds_dwordx4 v[192:193], off
	s_waitcnt vmcnt(8)
	s_waitcnt lgkmcnt(0)
	s_barrier
	s_setprio 1
	s_waitcnt lgkmcnt(0)
	v_mfma_f32_16x16x32_bf16 v[126:129], v[148:151], v[180:183], 0
	v_mfma_f32_16x16x32_bf16 v[122:125], v[156:159], v[180:183], 0
	v_mfma_f32_16x16x32_bf16 v[114:117], v[148:151], v[188:191], 0
	v_mfma_f32_16x16x32_bf16 v[106:109], v[156:159], v[188:191], 0
	v_mfma_f32_16x16x32_bf16 v[98:101], v[148:151], v[206:209], 0
	v_mfma_f32_16x16x32_bf16 v[88:91], v[156:159], v[206:209], 0
	v_mfma_f32_16x16x32_bf16 v[80:83], v[148:151], v[214:217], 0
	v_mfma_f32_16x16x32_bf16 v[72:75], v[156:159], v[214:217], 0
	v_mfma_f32_16x16x32_bf16 v[126:129], v[152:155], v[184:187], v[126:129]
	v_mfma_f32_16x16x32_bf16 v[122:125], v[160:163], v[184:187], v[122:125]
	v_mfma_f32_16x16x32_bf16 v[114:117], v[152:155], v[202:205], v[114:117]
	v_mfma_f32_16x16x32_bf16 v[106:109], v[160:163], v[202:205], v[106:109]
	v_mfma_f32_16x16x32_bf16 v[98:101], v[152:155], v[210:213], v[98:101]
	v_mfma_f32_16x16x32_bf16 v[88:91], v[160:163], v[210:213], v[88:91]
	v_mfma_f32_16x16x32_bf16 v[80:83], v[152:155], v[218:221], v[80:83]
	v_mfma_f32_16x16x32_bf16 v[72:75], v[160:163], v[218:221], v[72:75]
	s_setprio 0
	s_setprio 1
	v_mfma_f32_16x16x32_bf16 v[118:121], v[164:167], v[180:183], 0
	v_mfma_f32_16x16x32_bf16 v[110:113], v[172:175], v[180:183], 0
	v_mfma_f32_16x16x32_bf16 v[102:105], v[164:167], v[188:191], 0
	v_mfma_f32_16x16x32_bf16 v[92:95], v[172:175], v[188:191], 0
	v_mfma_f32_16x16x32_bf16 v[84:87], v[164:167], v[206:209], 0
	v_mfma_f32_16x16x32_bf16 v[76:79], v[172:175], v[206:209], 0
	v_mfma_f32_16x16x32_bf16 v[68:71], v[164:167], v[214:217], 0
	v_mfma_f32_16x16x32_bf16 v[64:67], v[172:175], v[214:217], 0
	v_mfma_f32_16x16x32_bf16 v[118:121], v[168:171], v[184:187], v[118:121]
	v_mfma_f32_16x16x32_bf16 v[110:113], v[176:179], v[184:187], v[110:113]
	v_mfma_f32_16x16x32_bf16 v[102:105], v[168:171], v[202:205], v[102:105]
	v_mfma_f32_16x16x32_bf16 v[92:95], v[176:179], v[202:205], v[92:95]
	v_mfma_f32_16x16x32_bf16 v[84:87], v[168:171], v[210:213], v[84:87]
	v_mfma_f32_16x16x32_bf16 v[76:79], v[176:179], v[210:213], v[76:79]
	v_mfma_f32_16x16x32_bf16 v[68:71], v[168:171], v[218:221], v[68:71]
	v_mfma_f32_16x16x32_bf16 v[64:67], v[176:179], v[218:221], v[64:67]
	s_setprio 0
	s_barrier
	s_add_i32 s18, s51, s34
	v_lshl_add_u64 v[192:193], s[22:23], 0, v[96:97]
	s_mov_b32 m0, s18
	ds_read_b128 v[180:183], v146 offset:16384
	ds_read_b128 v[184:187], v146 offset:17408
	ds_read_b128 v[188:191], v146 offset:18432
	ds_read_b128 v[202:205], v146 offset:19456
	ds_read_b128 v[206:209], v146 offset:20480
	ds_read_b128 v[210:213], v146 offset:21504
	ds_read_b128 v[214:217], v146 offset:22528
	ds_read_b128 v[218:221], v146 offset:23552
	global_load_lds_dwordx4 v[192:193], off
	s_add_i32 m0, s18, 0x2000
	s_add_u32 s18, s22, 0x18000
	v_lshl_add_u64 v[194:195], s[22:23], 0, v[130:131]
	s_addc_u32 s19, s23, 0
	s_add_i32 s51, s52, s34
	global_load_lds_dwordx4 v[194:195], off
	v_lshl_add_u64 v[196:197], s[18:19], 0, v[96:97]
	s_mov_b32 m0, s51
	v_lshl_add_u64 v[198:199], s[24:25], 0, v[132:133]
	global_load_lds_dwordx4 v[196:197], off
	v_lshl_add_u64 v[196:197], s[18:19], 0, v[130:131]
	s_add_i32 m0, s51, 0x2000
	s_nop 0
	global_load_lds_dwordx4 v[196:197], off
	v_lshl_add_u64 v[196:197], s[24:25], 0, v[134:135]
	s_mov_b32 m0, s35
	s_nop 0
	global_load_lds_dwordx4 v[196:197], off
	s_mov_b32 m0, s36
	s_nop 0
	global_load_lds_dwordx4 v[198:199], off
	s_waitcnt vmcnt(8)
	s_waitcnt lgkmcnt(0)
	s_barrier
	s_setprio 1
	s_waitcnt lgkmcnt(0)
	v_mfma_f32_16x16x32_bf16 v[60:63], v[148:151], v[180:183], 0
	v_mfma_f32_16x16x32_bf16 v[56:59], v[156:159], v[180:183], 0
	v_mfma_f32_16x16x32_bf16 v[48:51], v[148:151], v[188:191], 0
	v_mfma_f32_16x16x32_bf16 v[40:43], v[156:159], v[188:191], 0
	v_mfma_f32_16x16x32_bf16 v[32:35], v[148:151], v[206:209], 0
	v_mfma_f32_16x16x32_bf16 v[24:27], v[156:159], v[206:209], 0
	v_mfma_f32_16x16x32_bf16 v[16:19], v[148:151], v[214:217], 0
	v_mfma_f32_16x16x32_bf16 v[8:11], v[156:159], v[214:217], 0
	v_mfma_f32_16x16x32_bf16 v[60:63], v[152:155], v[184:187], v[60:63]
	v_mfma_f32_16x16x32_bf16 v[56:59], v[160:163], v[184:187], v[56:59]
	v_mfma_f32_16x16x32_bf16 v[48:51], v[152:155], v[202:205], v[48:51]
	v_mfma_f32_16x16x32_bf16 v[40:43], v[160:163], v[202:205], v[40:43]
	v_mfma_f32_16x16x32_bf16 v[32:35], v[152:155], v[210:213], v[32:35]
	v_mfma_f32_16x16x32_bf16 v[24:27], v[160:163], v[210:213], v[24:27]
	v_mfma_f32_16x16x32_bf16 v[16:19], v[152:155], v[218:221], v[16:19]
	v_mfma_f32_16x16x32_bf16 v[8:11], v[160:163], v[218:221], v[8:11]
	s_setprio 0
	s_setprio 1
	v_mfma_f32_16x16x32_bf16 v[52:55], v[164:167], v[180:183], 0
	v_mfma_f32_16x16x32_bf16 v[44:47], v[172:175], v[180:183], 0
	v_mfma_f32_16x16x32_bf16 v[36:39], v[164:167], v[188:191], 0
	v_mfma_f32_16x16x32_bf16 v[28:31], v[172:175], v[188:191], 0
	v_mfma_f32_16x16x32_bf16 v[20:23], v[164:167], v[206:209], 0
	v_mfma_f32_16x16x32_bf16 v[12:15], v[172:175], v[206:209], 0
	v_mfma_f32_16x16x32_bf16 v[4:7], v[164:167], v[214:217], 0
	v_mfma_f32_16x16x32_bf16 v[0:3], v[172:175], v[214:217], 0
	v_mfma_f32_16x16x32_bf16 v[52:55], v[168:171], v[184:187], v[52:55]
	v_mfma_f32_16x16x32_bf16 v[44:47], v[176:179], v[184:187], v[44:47]
	v_mfma_f32_16x16x32_bf16 v[36:39], v[168:171], v[202:205], v[36:39]
	v_mfma_f32_16x16x32_bf16 v[28:31], v[176:179], v[202:205], v[28:31]
	v_mfma_f32_16x16x32_bf16 v[20:23], v[168:171], v[210:213], v[20:23]
	v_mfma_f32_16x16x32_bf16 v[12:15], v[176:179], v[210:213], v[12:15]
	v_mfma_f32_16x16x32_bf16 v[4:7], v[168:171], v[218:221], v[4:7]
	v_mfma_f32_16x16x32_bf16 v[0:3], v[176:179], v[218:221], v[0:3]
	s_setprio 0
	s_barrier
	s_add_i32 s51, 0, 0x18000
	v_add_u32_e32 v147, s51, v141
	s_add_i32 s52, 0, 0x1c000
	ds_read_b128 v[148:151], v147
	ds_read_b128 v[152:155], v147 offset:1024
	ds_read_b128 v[156:159], v147 offset:2048
	ds_read_b128 v[160:163], v147 offset:3072
	v_add_u32_e32 v147, s52, v141
	ds_read_b128 v[164:167], v147
	ds_read_b128 v[168:171], v147 offset:1024
	ds_read_b128 v[172:175], v147 offset:2048
	ds_read_b128 v[176:179], v147 offset:3072
	s_add_u32 s18, s24, 0x50000
	s_addc_u32 s19, s25, 0
	s_mov_b32 m0, s37
	v_lshl_add_u64 v[200:201], s[18:19], 0, v[134:135]
	ds_read_b128 v[180:183], v146 offset:32768
	ds_read_b128 v[184:187], v146 offset:33792
	ds_read_b128 v[188:191], v146 offset:34816
	ds_read_b128 v[202:205], v146 offset:35840
	ds_read_b128 v[206:209], v146 offset:36864
	ds_read_b128 v[210:213], v146 offset:37888
	ds_read_b128 v[214:217], v146 offset:38912
	ds_read_b128 v[218:221], v146 offset:39936
	global_load_lds_dwordx4 v[200:201], off
	v_lshl_add_u64 v[200:201], s[18:19], 0, v[132:133]
	s_mov_b32 m0, s38
	s_nop 0
	global_load_lds_dwordx4 v[200:201], off
	s_waitcnt vmcnt(8)
	s_waitcnt lgkmcnt(0)
	s_barrier
	s_setprio 1
	s_waitcnt lgkmcnt(0)
	v_mfma_f32_16x16x32_bf16 v[126:129], v[148:151], v[180:183], v[126:129]
	v_mfma_f32_16x16x32_bf16 v[122:125], v[156:159], v[180:183], v[122:125]
	v_mfma_f32_16x16x32_bf16 v[114:117], v[148:151], v[188:191], v[114:117]
	v_mfma_f32_16x16x32_bf16 v[106:109], v[156:159], v[188:191], v[106:109]
	v_mfma_f32_16x16x32_bf16 v[98:101], v[148:151], v[206:209], v[98:101]
	v_mfma_f32_16x16x32_bf16 v[88:91], v[156:159], v[206:209], v[88:91]
	v_mfma_f32_16x16x32_bf16 v[80:83], v[148:151], v[214:217], v[80:83]
	v_mfma_f32_16x16x32_bf16 v[72:75], v[156:159], v[214:217], v[72:75]
	v_mfma_f32_16x16x32_bf16 v[126:129], v[152:155], v[184:187], v[126:129]
	v_mfma_f32_16x16x32_bf16 v[122:125], v[160:163], v[184:187], v[122:125]
	v_mfma_f32_16x16x32_bf16 v[114:117], v[152:155], v[202:205], v[114:117]
	v_mfma_f32_16x16x32_bf16 v[106:109], v[160:163], v[202:205], v[106:109]
	v_mfma_f32_16x16x32_bf16 v[98:101], v[152:155], v[210:213], v[98:101]
	v_mfma_f32_16x16x32_bf16 v[88:91], v[160:163], v[210:213], v[88:91]
	v_mfma_f32_16x16x32_bf16 v[80:83], v[152:155], v[218:221], v[80:83]
	v_mfma_f32_16x16x32_bf16 v[72:75], v[160:163], v[218:221], v[72:75]
	s_setprio 0
	s_setprio 1
	v_mfma_f32_16x16x32_bf16 v[118:121], v[164:167], v[180:183], v[118:121]
	v_mfma_f32_16x16x32_bf16 v[110:113], v[172:175], v[180:183], v[110:113]
	v_mfma_f32_16x16x32_bf16 v[102:105], v[164:167], v[188:191], v[102:105]
	v_mfma_f32_16x16x32_bf16 v[92:95], v[172:175], v[188:191], v[92:95]
	v_mfma_f32_16x16x32_bf16 v[84:87], v[164:167], v[206:209], v[84:87]
	v_mfma_f32_16x16x32_bf16 v[76:79], v[172:175], v[206:209], v[76:79]
	v_mfma_f32_16x16x32_bf16 v[68:71], v[164:167], v[214:217], v[68:71]
	v_mfma_f32_16x16x32_bf16 v[64:67], v[172:175], v[214:217], v[64:67]
	v_mfma_f32_16x16x32_bf16 v[118:121], v[168:171], v[184:187], v[118:121]
	v_mfma_f32_16x16x32_bf16 v[110:113], v[176:179], v[184:187], v[110:113]
	v_mfma_f32_16x16x32_bf16 v[102:105], v[168:171], v[202:205], v[102:105]
	v_mfma_f32_16x16x32_bf16 v[92:95], v[176:179], v[202:205], v[92:95]
	v_mfma_f32_16x16x32_bf16 v[84:87], v[168:171], v[210:213], v[84:87]
	v_mfma_f32_16x16x32_bf16 v[76:79], v[176:179], v[210:213], v[76:79]
	v_mfma_f32_16x16x32_bf16 v[68:71], v[168:171], v[218:221], v[68:71]
	v_mfma_f32_16x16x32_bf16 v[64:67], v[176:179], v[218:221], v[64:67]
	s_setprio 0
	s_barrier
	s_add_i32 s18, s51, s34
	v_lshl_add_u64 v[192:193], v[192:193], 0, s[64:65]
	s_mov_b32 m0, s18
	ds_read_b128 v[180:183], v146 offset:49152
	ds_read_b128 v[184:187], v146 offset:50176
	ds_read_b128 v[188:191], v146 offset:51200
	ds_read_b128 v[202:205], v146 offset:52224
	ds_read_b128 v[206:209], v146 offset:53248
	ds_read_b128 v[210:213], v146 offset:54272
	ds_read_b128 v[214:217], v146 offset:55296
	ds_read_b128 v[218:221], v146 offset:56320
	global_load_lds_dwordx4 v[192:193], off
	s_add_i32 m0, s18, 0x2000
	s_add_u32 s18, s22, 0x18080
	v_lshl_add_u64 v[192:193], v[194:195], 0, s[64:65]
	s_addc_u32 s19, s23, 0
	s_add_i32 s22, s52, s34
	global_load_lds_dwordx4 v[192:193], off
	v_lshl_add_u64 v[192:193], s[18:19], 0, v[96:97]
	s_mov_b32 m0, s22
	s_nop 0
	global_load_lds_dwordx4 v[192:193], off
	v_lshl_add_u64 v[192:193], s[18:19], 0, v[130:131]
	s_add_i32 m0, s22, 0x2000
	s_nop 0
	global_load_lds_dwordx4 v[192:193], off
	v_lshl_add_u64 v[192:193], v[196:197], 0, s[64:65]
	s_mov_b32 m0, s39
	s_nop 0
	global_load_lds_dwordx4 v[192:193], off
	v_lshl_add_u64 v[192:193], v[198:199], 0, s[64:65]
	s_mov_b32 m0, s40
	s_nop 0
	global_load_lds_dwordx4 v[192:193], off
	s_waitcnt vmcnt(8)
	s_waitcnt lgkmcnt(0)
	s_barrier
	s_setprio 1
	s_waitcnt lgkmcnt(0)
	v_mfma_f32_16x16x32_bf16 v[60:63], v[148:151], v[180:183], v[60:63]
	v_mfma_f32_16x16x32_bf16 v[56:59], v[156:159], v[180:183], v[56:59]
	v_mfma_f32_16x16x32_bf16 v[48:51], v[148:151], v[188:191], v[48:51]
	v_mfma_f32_16x16x32_bf16 v[40:43], v[156:159], v[188:191], v[40:43]
	v_mfma_f32_16x16x32_bf16 v[32:35], v[148:151], v[206:209], v[32:35]
	v_mfma_f32_16x16x32_bf16 v[24:27], v[156:159], v[206:209], v[24:27]
	v_mfma_f32_16x16x32_bf16 v[16:19], v[148:151], v[214:217], v[16:19]
	v_mfma_f32_16x16x32_bf16 v[8:11], v[156:159], v[214:217], v[8:11]
	v_mfma_f32_16x16x32_bf16 v[60:63], v[152:155], v[184:187], v[60:63]
	v_mfma_f32_16x16x32_bf16 v[56:59], v[160:163], v[184:187], v[56:59]
	v_mfma_f32_16x16x32_bf16 v[48:51], v[152:155], v[202:205], v[48:51]
	v_mfma_f32_16x16x32_bf16 v[40:43], v[160:163], v[202:205], v[40:43]
	v_mfma_f32_16x16x32_bf16 v[32:35], v[152:155], v[210:213], v[32:35]
	v_mfma_f32_16x16x32_bf16 v[24:27], v[160:163], v[210:213], v[24:27]
	v_mfma_f32_16x16x32_bf16 v[16:19], v[152:155], v[218:221], v[16:19]
	v_mfma_f32_16x16x32_bf16 v[8:11], v[160:163], v[218:221], v[8:11]
	s_setprio 0
	s_setprio 1
	v_mfma_f32_16x16x32_bf16 v[52:55], v[164:167], v[180:183], v[52:55]
	v_mfma_f32_16x16x32_bf16 v[44:47], v[172:175], v[180:183], v[44:47]
	v_mfma_f32_16x16x32_bf16 v[36:39], v[164:167], v[188:191], v[36:39]
	v_mfma_f32_16x16x32_bf16 v[28:31], v[172:175], v[188:191], v[28:31]
	v_mfma_f32_16x16x32_bf16 v[20:23], v[164:167], v[206:209], v[20:23]
	v_mfma_f32_16x16x32_bf16 v[12:15], v[172:175], v[206:209], v[12:15]
	v_mfma_f32_16x16x32_bf16 v[4:7], v[164:167], v[214:217], v[4:7]
	v_mfma_f32_16x16x32_bf16 v[0:3], v[172:175], v[214:217], v[0:3]
	v_mfma_f32_16x16x32_bf16 v[52:55], v[168:171], v[184:187], v[52:55]
	v_mfma_f32_16x16x32_bf16 v[44:47], v[176:179], v[184:187], v[44:47]
	v_mfma_f32_16x16x32_bf16 v[36:39], v[168:171], v[202:205], v[36:39]
	v_mfma_f32_16x16x32_bf16 v[28:31], v[176:179], v[202:205], v[28:31]
	v_mfma_f32_16x16x32_bf16 v[20:23], v[168:171], v[210:213], v[20:23]
	v_mfma_f32_16x16x32_bf16 v[12:15], v[176:179], v[210:213], v[12:15]
	v_mfma_f32_16x16x32_bf16 v[4:7], v[168:171], v[218:221], v[4:7]
	v_mfma_f32_16x16x32_bf16 v[0:3], v[176:179], v[218:221], v[0:3]
	s_setprio 0
	s_barrier
	s_add_i32 s50, s50, 2
	s_add_u32 s48, s48, 0x100
	s_addc_u32 s49, s49, 0
	s_cmp_gt_u32 s50, 3
	s_mov_b64 s[18:19], s[20:21]
	s_cbranch_scc1 .Lpeel_done_861
	.p2align 6

.LBB0_1236:
	s_ashr_i32 s17, s16, 31
	s_lshl_b64 s[18:19], s[16:17], 19
	s_add_u32 s18, s35, s18
	s_addc_u32 s19, s36, s19
	s_and_b64 s[20:21], s[4:5], exec
	s_cselect_b32 s17, s19, s27
	s_cselect_b32 s23, s18, s26
	s_ashr_i32 s15, s14, 31
	s_lshl_b64 s[20:21], s[14:15], 19
	s_add_u32 s20, s37, s20
	s_addc_u32 s21, s38, s21
	s_and_b64 s[30:31], s[4:5], exec
	s_cselect_b32 s15, s21, s29
	s_cselect_b32 s25, s20, s28
	s_add_u32 s26, s26, 0x40080
	s_addc_u32 s27, s27, 0
	s_add_u32 s49, s28, 0x100
	s_addc_u32 s50, s29, 0
	s_mov_b32 s51, -2
	s_waitcnt vmcnt(0)
	s_add_u32 s28, s26, 0xfffc0080
	s_addc_u32 s29, s27, -1
	s_add_i32 s52, 0, 0x10000
	s_cmp_eq_u32 s51, 12
	s_cselect_b32 s31, s17, s29
	s_cselect_b32 s30, s23, s28
	s_cselect_b32 s29, s15, s50
	s_cselect_b32 s28, s25, s49
	s_add_i32 s54, 0, 0x14000
	v_add_u32_e32 v134, s52, v245
	v_add_u32_e32 v150, s54, v245
	ds_read_b128 v[122:125], v134
	ds_read_b128 v[126:129], v134 offset:1024
	ds_read_b128 v[130:133], v134 offset:2048
	ds_read_b128 v[134:137], v134 offset:3072
	ds_read_b128 v[138:141], v150
	ds_read_b128 v[142:145], v150 offset:1024
	ds_read_b128 v[146:149], v150 offset:2048
	ds_read_b128 v[150:153], v150 offset:3072
	v_lshl_add_u64 v[194:195], s[26:27], 0, v[204:205]
	s_add_i32 m0, s40, 0xc000
	ds_read_b128 v[162:165], v199
	ds_read_b128 v[166:169], v199 offset:1024
	ds_read_b128 v[170:173], v199 offset:2048
	ds_read_b128 v[174:177], v199 offset:3072
	ds_read_b128 v[178:181], v199 offset:4096
	ds_read_b128 v[182:185], v199 offset:5120
	ds_read_b128 v[186:189], v199 offset:6144
	ds_read_b128 v[208:211], v199 offset:7168
	global_load_lds_dwordx4 v[194:195], off
	v_lshl_add_u64 v[194:195], s[26:27], 0, v[206:207]
	s_add_i32 m0, s40, 0xe000
	s_nop 0
	global_load_lds_dwordx4 v[194:195], off
	s_waitcnt vmcnt(8)
	s_waitcnt lgkmcnt(0)
	s_barrier
	s_setprio 1
	s_waitcnt lgkmcnt(0)
	v_mfma_f32_16x16x32_bf16 v[158:161], v[122:125], v[162:165], 0
	v_mfma_f32_16x16x32_bf16 v[154:157], v[130:133], v[162:165], 0
	v_mfma_f32_16x16x32_bf16 v[110:113], v[122:125], v[170:173], 0
	v_mfma_f32_16x16x32_bf16 v[106:109], v[130:133], v[170:173], 0
	v_mfma_f32_16x16x32_bf16 v[92:95], v[122:125], v[178:181], 0
	v_mfma_f32_16x16x32_bf16 v[88:91], v[130:133], v[178:181], 0
	v_mfma_f32_16x16x32_bf16 v[76:79], v[122:125], v[186:189], 0
	v_mfma_f32_16x16x32_bf16 v[72:75], v[130:133], v[186:189], 0
	v_mfma_f32_16x16x32_bf16 v[158:161], v[126:129], v[166:169], v[158:161]
	v_mfma_f32_16x16x32_bf16 v[154:157], v[134:137], v[166:169], v[154:157]
	v_mfma_f32_16x16x32_bf16 v[110:113], v[126:129], v[174:177], v[110:113]
	v_mfma_f32_16x16x32_bf16 v[106:109], v[134:137], v[174:177], v[106:109]
	v_mfma_f32_16x16x32_bf16 v[92:95], v[126:129], v[182:185], v[92:95]
	v_mfma_f32_16x16x32_bf16 v[88:91], v[134:137], v[182:185], v[88:91]
	v_mfma_f32_16x16x32_bf16 v[76:79], v[126:129], v[208:211], v[76:79]
	v_mfma_f32_16x16x32_bf16 v[72:75], v[134:137], v[208:211], v[72:75]
	s_setprio 0
	s_setprio 1
	v_mfma_f32_16x16x32_bf16 v[118:121], v[138:141], v[162:165], 0
	v_mfma_f32_16x16x32_bf16 v[114:117], v[146:149], v[162:165], 0
	v_mfma_f32_16x16x32_bf16 v[102:105], v[138:141], v[170:173], 0
	v_mfma_f32_16x16x32_bf16 v[98:101], v[146:149], v[170:173], 0
	v_mfma_f32_16x16x32_bf16 v[84:87], v[138:141], v[178:181], 0
	v_mfma_f32_16x16x32_bf16 v[80:83], v[146:149], v[178:181], 0
	v_mfma_f32_16x16x32_bf16 v[68:71], v[138:141], v[186:189], 0
	v_mfma_f32_16x16x32_bf16 v[64:67], v[146:149], v[186:189], 0
	v_mfma_f32_16x16x32_bf16 v[118:121], v[142:145], v[166:169], v[118:121]
	v_mfma_f32_16x16x32_bf16 v[114:117], v[150:153], v[166:169], v[114:117]
	v_mfma_f32_16x16x32_bf16 v[102:105], v[142:145], v[174:177], v[102:105]
	v_mfma_f32_16x16x32_bf16 v[98:101], v[150:153], v[174:177], v[98:101]
	v_mfma_f32_16x16x32_bf16 v[84:87], v[142:145], v[182:185], v[84:87]
	v_mfma_f32_16x16x32_bf16 v[80:83], v[150:153], v[182:185], v[80:83]
	v_mfma_f32_16x16x32_bf16 v[68:71], v[142:145], v[208:211], v[68:71]
	v_mfma_f32_16x16x32_bf16 v[64:67], v[150:153], v[208:211], v[64:67]
	s_setprio 0
	s_barrier
	s_add_i32 s52, s52, s39
	v_lshl_add_u64 v[194:195], s[28:29], 0, v[96:97]
	s_mov_b32 m0, s52
	ds_read_b128 v[162:165], v199 offset:16384
	ds_read_b128 v[166:169], v199 offset:17408
	ds_read_b128 v[170:173], v199 offset:18432
	ds_read_b128 v[174:177], v199 offset:19456
	ds_read_b128 v[178:181], v199 offset:20480
	ds_read_b128 v[182:185], v199 offset:21504
	ds_read_b128 v[186:189], v199 offset:22528
	ds_read_b128 v[208:211], v199 offset:23552
	global_load_lds_dwordx4 v[194:195], off
	s_add_i32 m0, s52, 0x2000
	s_add_u32 s52, s28, 0x40000
	v_lshl_add_u64 v[196:197], s[28:29], 0, v[202:203]
	s_addc_u32 s53, s29, 0
	s_add_i32 s54, s54, s39
	global_load_lds_dwordx4 v[196:197], off
	v_lshl_add_u64 v[200:201], s[52:53], 0, v[96:97]
	s_mov_b32 m0, s54
	v_lshl_add_u64 v[212:213], s[30:31], 0, v[192:193]
	global_load_lds_dwordx4 v[200:201], off
	v_lshl_add_u64 v[200:201], s[52:53], 0, v[202:203]
	s_add_i32 m0, s54, 0x2000
	s_nop 0
	global_load_lds_dwordx4 v[200:201], off
	v_lshl_add_u64 v[200:201], s[30:31], 0, v[190:191]
	s_mov_b32 m0, s40
	s_nop 0
	global_load_lds_dwordx4 v[200:201], off
	s_mov_b32 m0, s41
	s_nop 0
	global_load_lds_dwordx4 v[212:213], off
	s_waitcnt vmcnt(8)
	s_waitcnt lgkmcnt(0)
	s_barrier
	s_setprio 1
	s_waitcnt lgkmcnt(0)
	v_mfma_f32_16x16x32_bf16 v[60:63], v[122:125], v[162:165], 0
	v_mfma_f32_16x16x32_bf16 v[56:59], v[130:133], v[162:165], 0
	v_mfma_f32_16x16x32_bf16 v[44:47], v[122:125], v[170:173], 0
	v_mfma_f32_16x16x32_bf16 v[40:43], v[130:133], v[170:173], 0
	v_mfma_f32_16x16x32_bf16 v[28:31], v[122:125], v[178:181], 0
	v_mfma_f32_16x16x32_bf16 v[24:27], v[130:133], v[178:181], 0
	v_mfma_f32_16x16x32_bf16 v[12:15], v[122:125], v[186:189], 0
	v_mfma_f32_16x16x32_bf16 v[8:11], v[130:133], v[186:189], 0
	v_mfma_f32_16x16x32_bf16 v[60:63], v[126:129], v[166:169], v[60:63]
	v_mfma_f32_16x16x32_bf16 v[56:59], v[134:137], v[166:169], v[56:59]
	v_mfma_f32_16x16x32_bf16 v[44:47], v[126:129], v[174:177], v[44:47]
	v_mfma_f32_16x16x32_bf16 v[40:43], v[134:137], v[174:177], v[40:43]
	v_mfma_f32_16x16x32_bf16 v[28:31], v[126:129], v[182:185], v[28:31]
	v_mfma_f32_16x16x32_bf16 v[24:27], v[134:137], v[182:185], v[24:27]
	v_mfma_f32_16x16x32_bf16 v[12:15], v[126:129], v[208:211], v[12:15]
	v_mfma_f32_16x16x32_bf16 v[8:11], v[134:137], v[208:211], v[8:11]
	s_setprio 0
	s_setprio 1
	v_mfma_f32_16x16x32_bf16 v[52:55], v[138:141], v[162:165], 0
	v_mfma_f32_16x16x32_bf16 v[48:51], v[146:149], v[162:165], 0
	v_mfma_f32_16x16x32_bf16 v[36:39], v[138:141], v[170:173], 0
	v_mfma_f32_16x16x32_bf16 v[32:35], v[146:149], v[170:173], 0
	v_mfma_f32_16x16x32_bf16 v[20:23], v[138:141], v[178:181], 0
	v_mfma_f32_16x16x32_bf16 v[16:19], v[146:149], v[178:181], 0
	v_mfma_f32_16x16x32_bf16 v[4:7], v[138:141], v[186:189], 0
	v_mfma_f32_16x16x32_bf16 v[0:3], v[146:149], v[186:189], 0
	v_mfma_f32_16x16x32_bf16 v[52:55], v[142:145], v[166:169], v[52:55]
	v_mfma_f32_16x16x32_bf16 v[48:51], v[150:153], v[166:169], v[48:51]
	v_mfma_f32_16x16x32_bf16 v[36:39], v[142:145], v[174:177], v[36:39]
	v_mfma_f32_16x16x32_bf16 v[32:35], v[150:153], v[174:177], v[32:35]
	v_mfma_f32_16x16x32_bf16 v[20:23], v[142:145], v[182:185], v[20:23]
	v_mfma_f32_16x16x32_bf16 v[16:19], v[150:153], v[182:185], v[16:19]
	v_mfma_f32_16x16x32_bf16 v[4:7], v[142:145], v[208:211], v[4:7]
	v_mfma_f32_16x16x32_bf16 v[0:3], v[150:153], v[208:211], v[0:3]
	s_setprio 0
	s_barrier
	s_add_i32 s52, 0, 0x18000
	s_add_i32 s53, 0, 0x1c000
	v_add_u32_e32 v134, s52, v245
	v_add_u32_e32 v150, s53, v245
	ds_read_b128 v[122:125], v134
	ds_read_b128 v[126:129], v134 offset:1024
	ds_read_b128 v[130:133], v134 offset:2048
	ds_read_b128 v[134:137], v134 offset:3072
	ds_read_b128 v[138:141], v150
	ds_read_b128 v[142:145], v150 offset:1024
	ds_read_b128 v[146:149], v150 offset:2048
	ds_read_b128 v[150:153], v150 offset:3072
	s_add_u32 s30, s30, 0x40000
	s_addc_u32 s31, s31, 0
	s_mov_b32 m0, s42
	v_lshl_add_u64 v[214:215], s[30:31], 0, v[190:191]
	ds_read_b128 v[162:165], v199 offset:32768
	ds_read_b128 v[166:169], v199 offset:33792
	ds_read_b128 v[170:173], v199 offset:34816
	ds_read_b128 v[174:177], v199 offset:35840
	ds_read_b128 v[178:181], v199 offset:36864
	ds_read_b128 v[182:185], v199 offset:37888
	ds_read_b128 v[186:189], v199 offset:38912
	ds_read_b128 v[208:211], v199 offset:39936
	global_load_lds_dwordx4 v[214:215], off
	v_lshl_add_u64 v[214:215], s[30:31], 0, v[192:193]
	s_mov_b32 m0, s43
	s_nop 0
	global_load_lds_dwordx4 v[214:215], off
	s_waitcnt vmcnt(8)
	s_waitcnt lgkmcnt(0)
	s_barrier
	s_setprio 1
	s_waitcnt lgkmcnt(0)
	v_mfma_f32_16x16x32_bf16 v[158:161], v[122:125], v[162:165], v[158:161]
	v_mfma_f32_16x16x32_bf16 v[154:157], v[130:133], v[162:165], v[154:157]
	v_mfma_f32_16x16x32_bf16 v[110:113], v[122:125], v[170:173], v[110:113]
	v_mfma_f32_16x16x32_bf16 v[106:109], v[130:133], v[170:173], v[106:109]
	v_mfma_f32_16x16x32_bf16 v[92:95], v[122:125], v[178:181], v[92:95]
	v_mfma_f32_16x16x32_bf16 v[88:91], v[130:133], v[178:181], v[88:91]
	v_mfma_f32_16x16x32_bf16 v[76:79], v[122:125], v[186:189], v[76:79]
	v_mfma_f32_16x16x32_bf16 v[72:75], v[130:133], v[186:189], v[72:75]
	v_mfma_f32_16x16x32_bf16 v[158:161], v[126:129], v[166:169], v[158:161]
	v_mfma_f32_16x16x32_bf16 v[154:157], v[134:137], v[166:169], v[154:157]
	v_mfma_f32_16x16x32_bf16 v[110:113], v[126:129], v[174:177], v[110:113]
	v_mfma_f32_16x16x32_bf16 v[106:109], v[134:137], v[174:177], v[106:109]
	v_mfma_f32_16x16x32_bf16 v[92:95], v[126:129], v[182:185], v[92:95]
	v_mfma_f32_16x16x32_bf16 v[88:91], v[134:137], v[182:185], v[88:91]
	v_mfma_f32_16x16x32_bf16 v[76:79], v[126:129], v[208:211], v[76:79]
	v_mfma_f32_16x16x32_bf16 v[72:75], v[134:137], v[208:211], v[72:75]
	s_setprio 0
	s_setprio 1
	v_mfma_f32_16x16x32_bf16 v[118:121], v[138:141], v[162:165], v[118:121]
	v_mfma_f32_16x16x32_bf16 v[114:117], v[146:149], v[162:165], v[114:117]
	v_mfma_f32_16x16x32_bf16 v[102:105], v[138:141], v[170:173], v[102:105]
	v_mfma_f32_16x16x32_bf16 v[98:101], v[146:149], v[170:173], v[98:101]
	v_mfma_f32_16x16x32_bf16 v[84:87], v[138:141], v[178:181], v[84:87]
	v_mfma_f32_16x16x32_bf16 v[80:83], v[146:149], v[178:181], v[80:83]
	v_mfma_f32_16x16x32_bf16 v[68:71], v[138:141], v[186:189], v[68:71]
	v_mfma_f32_16x16x32_bf16 v[64:67], v[146:149], v[186:189], v[64:67]
	v_mfma_f32_16x16x32_bf16 v[118:121], v[142:145], v[166:169], v[118:121]
	v_mfma_f32_16x16x32_bf16 v[114:117], v[150:153], v[166:169], v[114:117]
	v_mfma_f32_16x16x32_bf16 v[102:105], v[142:145], v[174:177], v[102:105]
	v_mfma_f32_16x16x32_bf16 v[98:101], v[150:153], v[174:177], v[98:101]
	v_mfma_f32_16x16x32_bf16 v[84:87], v[142:145], v[182:185], v[84:87]
	v_mfma_f32_16x16x32_bf16 v[80:83], v[150:153], v[182:185], v[80:83]
	v_mfma_f32_16x16x32_bf16 v[68:71], v[142:145], v[208:211], v[68:71]
	v_mfma_f32_16x16x32_bf16 v[64:67], v[150:153], v[208:211], v[64:67]
	s_setprio 0
	s_barrier
	s_add_i32 s30, s52, s39
	v_lshl_add_u64 v[194:195], v[194:195], 0, s[64:65]
	s_mov_b32 m0, s30
	ds_read_b128 v[162:165], v199 offset:49152
	ds_read_b128 v[166:169], v199 offset:50176
	ds_read_b128 v[170:173], v199 offset:51200
	ds_read_b128 v[174:177], v199 offset:52224
	ds_read_b128 v[178:181], v199 offset:53248
	ds_read_b128 v[182:185], v199 offset:54272
	ds_read_b128 v[186:189], v199 offset:55296
	ds_read_b128 v[208:211], v199 offset:56320
	global_load_lds_dwordx4 v[194:195], off
	s_add_i32 m0, s30, 0x2000
	s_add_u32 s28, s28, 0x40080
	v_lshl_add_u64 v[194:195], v[196:197], 0, s[64:65]
	s_addc_u32 s29, s29, 0
	s_add_i32 s30, s53, s39
	global_load_lds_dwordx4 v[194:195], off
	v_lshl_add_u64 v[194:195], s[28:29], 0, v[96:97]
	s_mov_b32 m0, s30
	s_nop 0
	global_load_lds_dwordx4 v[194:195], off
	v_lshl_add_u64 v[194:195], s[28:29], 0, v[202:203]
	s_add_i32 m0, s30, 0x2000
	s_nop 0
	global_load_lds_dwordx4 v[194:195], off
	v_lshl_add_u64 v[194:195], v[200:201], 0, s[64:65]
	s_mov_b32 m0, s45
	s_nop 0
	global_load_lds_dwordx4 v[194:195], off
	v_lshl_add_u64 v[194:195], v[212:213], 0, s[64:65]
	s_mov_b32 m0, s46
	s_nop 0
	global_load_lds_dwordx4 v[194:195], off
	s_waitcnt vmcnt(8)
	s_waitcnt lgkmcnt(0)
	s_barrier
	s_setprio 1
	s_waitcnt lgkmcnt(0)
	v_mfma_f32_16x16x32_bf16 v[60:63], v[122:125], v[162:165], v[60:63]
	v_mfma_f32_16x16x32_bf16 v[56:59], v[130:133], v[162:165], v[56:59]
	v_mfma_f32_16x16x32_bf16 v[44:47], v[122:125], v[170:173], v[44:47]
	v_mfma_f32_16x16x32_bf16 v[40:43], v[130:133], v[170:173], v[40:43]
	v_mfma_f32_16x16x32_bf16 v[28:31], v[122:125], v[178:181], v[28:31]
	v_mfma_f32_16x16x32_bf16 v[24:27], v[130:133], v[178:181], v[24:27]
	v_mfma_f32_16x16x32_bf16 v[12:15], v[122:125], v[186:189], v[12:15]
	v_mfma_f32_16x16x32_bf16 v[8:11], v[130:133], v[186:189], v[8:11]
	v_mfma_f32_16x16x32_bf16 v[60:63], v[126:129], v[166:169], v[60:63]
	v_mfma_f32_16x16x32_bf16 v[56:59], v[134:137], v[166:169], v[56:59]
	v_mfma_f32_16x16x32_bf16 v[44:47], v[126:129], v[174:177], v[44:47]
	v_mfma_f32_16x16x32_bf16 v[40:43], v[134:137], v[174:177], v[40:43]
	v_mfma_f32_16x16x32_bf16 v[28:31], v[126:129], v[182:185], v[28:31]
	v_mfma_f32_16x16x32_bf16 v[24:27], v[134:137], v[182:185], v[24:27]
	v_mfma_f32_16x16x32_bf16 v[12:15], v[126:129], v[208:211], v[12:15]
	v_mfma_f32_16x16x32_bf16 v[8:11], v[134:137], v[208:211], v[8:11]
	s_setprio 0
	s_setprio 1
	v_mfma_f32_16x16x32_bf16 v[52:55], v[138:141], v[162:165], v[52:55]
	v_mfma_f32_16x16x32_bf16 v[48:51], v[146:149], v[162:165], v[48:51]
	v_mfma_f32_16x16x32_bf16 v[36:39], v[138:141], v[170:173], v[36:39]
	v_mfma_f32_16x16x32_bf16 v[32:35], v[146:149], v[170:173], v[32:35]
	v_mfma_f32_16x16x32_bf16 v[20:23], v[138:141], v[178:181], v[20:23]
	v_mfma_f32_16x16x32_bf16 v[16:19], v[146:149], v[178:181], v[16:19]
	v_mfma_f32_16x16x32_bf16 v[4:7], v[138:141], v[186:189], v[4:7]
	v_mfma_f32_16x16x32_bf16 v[0:3], v[146:149], v[186:189], v[0:3]
	v_mfma_f32_16x16x32_bf16 v[52:55], v[142:145], v[166:169], v[52:55]
	v_mfma_f32_16x16x32_bf16 v[48:51], v[150:153], v[166:169], v[48:51]
	v_mfma_f32_16x16x32_bf16 v[36:39], v[142:145], v[174:177], v[36:39]
	v_mfma_f32_16x16x32_bf16 v[32:35], v[150:153], v[174:177], v[32:35]
	v_mfma_f32_16x16x32_bf16 v[20:23], v[142:145], v[182:185], v[20:23]
	v_mfma_f32_16x16x32_bf16 v[16:19], v[150:153], v[182:185], v[16:19]
	v_mfma_f32_16x16x32_bf16 v[4:7], v[142:145], v[208:211], v[4:7]
	v_mfma_f32_16x16x32_bf16 v[0:3], v[150:153], v[208:211], v[0:3]
	s_setprio 0
	s_barrier
	s_add_i32 s51, s51, 2
	s_add_u32 s26, s26, 0x100
	s_addc_u32 s27, s27, 0
	s_add_u32 s49, s49, 0x100
	s_addc_u32 s50, s50, 0
	s_cmp_gt_u32 s51, 13
	s_cbranch_scc1 .Lpeel_done_1237
	.p2align 6
